# LN rewrite + MoBA K/V flat loads to global loads + cvt_panel loads batched 8-deep
# speedup vs baseline: 1.0003x; 1.0003x over previous
; __device__ __forceinline__ unsigned pk2(float lo, float hi) { return pg8::cvt_pk_bf16(lo, hi); }
; __device__ __forceinline__ void cvt_panel(int pm, const float* x, bf16* xb) {
;     ...
;     for (int i = tid; i < 256 * DM / 8; i += NTHR) { const f32x4 a = *(const f32x4*)(src + (size_t)i * 8), b = *(const f32x4*)(src + (size_t)i * 8 + 4);
;         u32x4 w; w.x = pk2(a.x, a.y); w.y = pk2(a.z, a.w); w.z = pk2(b.x, b.y); w.w = pk2(b.z, b.w); *(u32x4*)(dst + (size_t)i * 8) = w; }
.LBB0_58:
	global_load_dwordx4 v[28:31], v[10:11], off
	global_load_dwordx4 v[32:35], v[10:11], off offset:16
	global_load_dwordx4 v[36:39], v[16:17], off
	global_load_dwordx4 v[40:43], v[16:17], off offset:16
	global_load_dwordx4 v[44:47], v[12:13], off
	global_load_dwordx4 v[48:51], v[12:13], off offset:16
	global_load_dwordx4 v[52:55], v[6:7], off
	global_load_dwordx4 v[56:59], v[6:7], off offset:16
	v_lshl_add_u64 v[18:19], s[24:25], 0, v[4:5]
	v_lshl_add_u64 v[20:21], s[24:25], 0, v[14:15]
	v_lshl_add_u64 v[22:23], s[24:25], 0, v[8:9]
	v_lshl_add_u64 v[24:25], s[24:25], 0, v[2:3]
	v_add_u32_e32 v1, 0x800, v1
	v_cmp_lt_i32_e32 vcc, s29, v1
	v_lshl_add_u64 v[10:11], v[10:11], 0, s[18:19]
	v_lshl_add_u64 v[16:17], v[16:17], 0, s[18:19]
	v_lshl_add_u64 v[12:13], v[12:13], 0, s[18:19]
	v_lshl_add_u64 v[6:7], v[6:7], 0, s[18:19]
	s_add_u32 s24, s24, 0x8000
	s_addc_u32 s25, s25, 0
	s_or_b64 s[22:23], vcc, s[22:23]
	s_waitcnt vmcnt(6)
	v_cvt_pk_bf16_f32 v28, v28, v29
	v_cvt_pk_bf16_f32 v29, v30, v31
	v_cvt_pk_bf16_f32 v30, v32, v33
	v_cvt_pk_bf16_f32 v31, v34, v35
	global_store_dwordx4 v[18:19], v[28:31], off
	s_waitcnt vmcnt(5)
	v_cvt_pk_bf16_f32 v36, v36, v37
	v_cvt_pk_bf16_f32 v37, v38, v39
	v_cvt_pk_bf16_f32 v38, v40, v41
	v_cvt_pk_bf16_f32 v39, v42, v43
	global_store_dwordx4 v[20:21], v[36:39], off
	s_waitcnt vmcnt(4)
	v_cvt_pk_bf16_f32 v44, v44, v45
	v_cvt_pk_bf16_f32 v45, v46, v47
	v_cvt_pk_bf16_f32 v46, v48, v49
	v_cvt_pk_bf16_f32 v47, v50, v51
	global_store_dwordx4 v[22:23], v[44:47], off
	s_waitcnt vmcnt(3)
	v_cvt_pk_bf16_f32 v52, v52, v53
	v_cvt_pk_bf16_f32 v53, v54, v55
	v_cvt_pk_bf16_f32 v54, v56, v57
	v_cvt_pk_bf16_f32 v55, v58, v59
	global_store_dwordx4 v[24:25], v[52:55], off
	s_andn2_b64 exec, exec, s[22:23]
	s_cbranch_execnz .LBB0_58
	s_branch .LBB0_50

; __device__ __forceinline__ unsigned pk2(float lo, float hi) { return pg8::cvt_pk_bf16(lo, hi); }
; #define TASK_ADV() do { have = false; for (;;) { ++ch; ++k; while (n < qb && ch >= ((c + 31) >> 5)) { ++n; ch = 0; c = (n < qb) ? (int)CNT[n] : 0; } \
;                         if (n >= qb) break; if ((k & 7) == wave) { have = true; break; } } } while (0)
; #define TASK_Q(Q2, VALID, QG) do { const int idx_ = ch * 32 + r32; VALID = idx_ < c; Q2 = (int)LIST[n * 256 + (VALID ? idx_ : ch * 32)]; \
;                         const bf16* qp_ = qkv + ((size_t)b * SEQ + 256 * qb + Q2) * PA + C_CQ + h * 64 + hi * 8; \
;                         _Pragma("unroll") for (int d0 = 0; d0 < 4; ++d0) QG[d0] = *(const bf16x8*)(qp_ + 16 * d0); } while (0)
; __device__ __forceinline__ void moba_unit(int b, int h, int qb, const bf16* qkv, const bf16* KF, const bf16* VF, bf16* Y, const float* kmean, LAS unsigned char* lds) {
;     ...
;         { const float xs = sl2 * (1.f / (0.125f * LOG2E)); const unsigned shb = pk2(xs, 0.f) & 0xffffu; const float res = xs - __uint_as_float(shb << 16);
;           const unsigned qw = (hi == 0) ? (shb | (pk2(res, 0.f) << 16)) : 0u;
;           const unsigned k0w = (hi == 0) ? pk2((float)r32, (float)r32) : 0u, k1w = (hi == 0) ? pk2((float)(r32 + 32), (float)(r32 + 32)) : 0u;
;           qx = __builtin_bit_cast(bf16x8, (u32x4){qw, 0u, 0u, 0u}); kx0 = __builtin_bit_cast(bf16x8, (u32x4){k0w, 0u, 0u, 0u}); kx1 = __builtin_bit_cast(bf16x8, (u32x4){k1w, 0u, 0u, 0u}); }
;         int n = 0, ch = -1, k = -1, c = (qb > 0) ? (int)CNT[0] : 0; bool have = false;
;     ...
;         TASK_ADV();
;         bf16x8 qg[4]; int q2 = 0; bool valid = false; KFr k0, k1; VFr v0; u32x4 pw[4];
;         const char* kp = (const char*)KFh + lane * 16; const char* vp = (const char*)VFh + lane * 16;
;         if (have) { TASK_Q(q2, valid, qg); kp += (size_t)(4 * n) * 8192; asm volatile("" : "+v"(kp)); loadK(k0, kp); }
.LBB0_232:
	s_andn2_b64 vcc, exec, s[2:3]
	s_cbranch_vccz .LBB0_266
	v_and_b32_e32 v232, 31, v0
	s_lshl_b32 s2, s25, 5
	s_waitcnt lgkmcnt(0)
	v_or_b32_e32 v2, s2, v232
	s_lshl_b32 s12, s24, 8
	v_mov_b32_e32 v3, s2
	v_cmp_lt_i32_e64 s[2:3], v2, v231
	s_add_i32 s12, s12, 0
	v_lshlrev_b32_e32 v64, 4, v1
	v_cndmask_b32_e64 v2, v3, v2, s[2:3]
	v_add_u32_e32 v2, s12, v2
	v_add_u32_e32 v2, 0x1b000, v2
	ds_read_u8 v216, v2
	v_readlane_b32 s14, v252, 59
	v_mov_b64_e32 v[2:3], s[36:37]
	s_movk_i32 s12, 0x1e00
	v_readlane_b32 s15, v252, 60
	s_waitcnt lgkmcnt(0)
	v_or_b32_e32 v1, s21, v216
	v_or_b32_e32 v1, s14, v1
	v_mad_u64_u32 v[2:3], s[12:13], v1, s12, v[2:3]
	v_lshrrev_b32_e32 v0, 2, v0
	v_mad_i32_i24 v3, s15, v226, v3
	s_lshl_b32 s46, s19, 1
	v_and_b32_e32 v0, 8, v0
	v_lshl_add_u64 v[2:3], v[2:3], 0, s[46:47]
	s_waitcnt vmcnt(0)
	v_lshlrev_b32_e32 v4, 1, v0
	v_mov_b32_e32 v5, v65
	v_lshl_add_u64 v[2:3], v[2:3], 0, v[4:5]
	s_mov_b64 s[12:13], 0x1200
	v_lshl_add_u64 v[4:5], v[2:3], 0, s[12:13]
	s_movk_i32 s12, 0x1000
	v_add_co_u32_e32 v2, vcc, s12, v2
	s_lshl_b32 s12, s24, 2
	s_ashr_i32 s13, s12, 31
	v_lshl_add_u64 v[208:209], s[10:11], 0, v[64:65]
	v_addc_co_u32_e32 v3, vcc, 0, v3, vcc
	s_lshl_b64 s[12:13], s[12:13], 13
	global_load_dwordx4 v[78:81], v[4:5], off offset:32
	global_load_dwordx4 v[82:85], v[4:5], off offset:64
	global_load_dwordx4 v[86:89], v[2:3], off offset:512
	global_load_dwordx4 v[90:93], v[4:5], off offset:96
	v_lshl_add_u64 v[2:3], v[208:209], 0, s[12:13]
	global_load_dwordx4 v[106:109], v[2:3], off
	global_load_dwordx4 v[102:105], v[2:3], off offset:1024
	global_load_dwordx4 v[98:101], v[2:3], off offset:2048
	global_load_dwordx4 v[94:97], v[2:3], off offset:3072
	v_lshl_add_u64 v[2:3], v[2:3], 0, s[56:57]
	global_load_dwordx4 v[122:125], v[2:3], off
	global_load_dwordx4 v[118:121], v[2:3], off offset:1024
	global_load_dwordx4 v[114:117], v[2:3], off offset:2048
	global_load_dwordx4 v[110:113], v[2:3], off offset:3072
	v_cvt_f32_ubyte0_e32 v1, v232
	v_cvt_pk_bf16_f32 v1, v1, v1
	v_cndmask_b32_e64 v70, 0, v1, s[0:1]
	v_or_b32_e32 v1, 32, v232
	v_cvt_f32_ubyte0_e32 v1, v1
	v_cvt_pk_bf16_f32 v1, v1, v1
	v_cndmask_b32_e64 v74, 0, v1, s[0:1]
	v_mov_b32_e32 v67, v65
	v_mov_b32_e32 v68, v65
	v_mov_b32_e32 v69, v65
	v_mov_b32_e32 v71, v65
	v_mov_b32_e32 v72, v65
	v_mov_b32_e32 v73, v65
	v_mov_b32_e32 v75, v65
	v_mov_b32_e32 v76, v65
	v_mov_b32_e32 v77, v65
	v_lshl_add_u64 v[214:215], v[2:3], 0, s[56:57]
	v_lshl_add_u64 v[210:211], s[6:7], 0, v[64:65]
	v_add_u32_e32 v233, 0, v0
	v_lshlrev_b32_e32 v212, 1, v0
	s_branch .LBB0_235

; #define SB_() __builtin_amdgcn_sched_barrier(0)
; __device__ __forceinline__ void tile_qk_fast(const KFr& f, const bf16x8 (&qf)[4], const bf16x8& kx0, const bf16x8& kx1, const bf16x8& qx, u32x4 (&pw)[4],
;                                              f32x16& o0, f32x16& o1, float& m, float& l, float off) {
;     ...
;     p0 = __builtin_amdgcn_mfma_f32_32x32x16_bf16(kx0, qx, p0, 0, 0, 0);
;     p1 = __builtin_amdgcn_mfma_f32_32x32x16_bf16(kx1, qx, p1, 0, 0, 0);
; #pragma unroll
;     for (int d0 = 0; d0 < 4; ++d0) {
;         p0 = __builtin_amdgcn_mfma_f32_32x32x16_bf16(f.a[0][d0], qf[d0], p0, 0, 0, 0);
;         p1 = __builtin_amdgcn_mfma_f32_32x32x16_bf16(f.a[1][d0], qf[d0], p1, 0, 0, 0);
;     }
;     constexpr float C2 = 0.125f * LOG2E;
;     float mr = fmaxf(p0[0], p1[0]);
; #pragma unroll
;     for (int r = 1; r < 16; ++r) mr = fmaxf(fmaxf(mr, p0[r]), p1[r]);
;     float mx = fmaf(mr, C2, off);
;     mx = fmaxf(mx, __shfl_xor(mx, 32));
;     const float mn = fmaxf(m, mx);
;     if (__ballot(mn > m) != 0ull) {
;         const float alpha = __builtin_amdgcn_exp2f(m - mn); l *= alpha;
; #pragma unroll
;         for (int r = 0; r < 16; ++r) { o0[r] *= alpha; o1[r] *= alpha; }
;     }
;     m = mn;
;     const float sh = off - mn;
;     float rs = 0.f;
; #pragma unroll
;     for (int r = 0; r < 16; ++r) { p0[r] = __builtin_amdgcn_exp2f(fmaf(p0[r], C2, sh)); p1[r] = __builtin_amdgcn_exp2f(fmaf(p1[r], C2, sh)); rs += p0[r] + p1[r]; }
; __device__ __forceinline__ void moba_unit(int b, int h, int qb, const bf16* qkv, const bf16* KF, const bf16* VF, bf16* Y, const float* kmean, LAS unsigned char* lds) {
;     ...
;             const int n_c = n; const bool valid_c = valid; const int q2_c = q2;
;             vp = (const char*)VFh + (size_t)(4 * n_c) * 8192 + lane * 16; asm volatile("" : "+v"(vp));
;             float m2 = -1e30f, l2 = 0.f; f32x16 a0, a1;
; #pragma unroll
;             for (int r = 0; r < 16; ++r) { a0[r] = 0.f; a1[r] = 0.f; }
;             const int kq0 = 256 * n_c - (256 * qb + q2_c);
;             TASK_ADV();
;             loadV(v0, vp); SB_();
;             loadK(k1, kp); SB_(); tile_qk_fast(k0, qg, kx0, kx1, qx, pw, a0, a1, m2, l2, sl2 * (float)(kq0)); SB_();
.LBB0_254:
	global_load_dwordx4 v[162:165], v[0:1], off
	global_load_dwordx4 v[154:157], v[0:1], off offset:1024
	global_load_dwordx4 v[146:149], v[0:1], off offset:2048
	global_load_dwordx4 v[142:145], v[0:1], off offset:3072
	v_lshl_add_u64 v[0:1], v[0:1], 0, s[56:57]
	global_load_dwordx4 v[170:173], v[0:1], off
	global_load_dwordx4 v[166:169], v[0:1], off offset:1024
	global_load_dwordx4 v[158:161], v[0:1], off offset:2048
	global_load_dwordx4 v[150:153], v[0:1], off offset:3072
	s_sub_i32 s2, s26, s20
	s_lshl_b32 s2, s2, 8
	v_sub_u32_e32 v236, s2, v234
	v_lshl_add_u64 v[216:217], v[0:1], 0, s[56:57]
	v_lshl_add_u64 v[0:1], v[214:215], 0, s[56:57]
	global_load_dwordx4 v[194:197], v[214:215], off
	global_load_dwordx4 v[186:189], v[214:215], off offset:1024
	global_load_dwordx4 v[182:185], v[214:215], off offset:2048
	global_load_dwordx4 v[174:177], v[214:215], off offset:3072
	global_load_dwordx4 v[202:205], v[0:1], off
	global_load_dwordx4 v[198:201], v[0:1], off offset:1024
	global_load_dwordx4 v[190:193], v[0:1], off offset:2048
	global_load_dwordx4 v[178:181], v[0:1], off offset:3072
	v_lshl_add_u64 v[218:219], v[0:1], 0, s[56:57]
	v_mfma_f32_32x32x16_bf16 v[48:63], v[70:73], v[66:69], 0
	v_cvt_f32_i32_e32 v64, v236
	s_mov_b32 s2, 0xf149f2ca
	s_waitcnt lgkmcnt(0)
	v_mfma_f32_32x32x16_bf16 v[32:47], v[74:77], v[66:69], 0
	s_waitcnt lgkmcnt(0)
	v_mfma_f32_32x32x16_bf16 v[16:31], v[106:109], v[138:141], v[48:63]
	v_mfma_f32_32x32x16_bf16 v[0:15], v[122:125], v[138:141], v[32:47]
	v_mfma_f32_32x32x16_bf16 v[16:31], v[102:105], v[134:137], v[16:31]
	v_mfma_f32_32x32x16_bf16 v[0:15], v[118:121], v[134:137], v[0:15]
	v_mfma_f32_32x32x16_bf16 v[16:31], v[98:101], v[130:133], v[16:31]
	v_mul_f32_e32 v98, v230, v64
	v_mfma_f32_32x32x16_bf16 v[0:15], v[114:117], v[130:133], v[0:15]
	v_mfma_f32_32x32x16_bf16 v[0:15], v[110:113], v[126:129], v[0:15]
	v_mfma_f32_32x32x16_bf16 v[16:31], v[94:97], v[126:129], v[16:31]
	s_nop 10
	v_max_f32_e32 v99, v0, v0
	v_max_f32_e32 v94, v16, v16
	v_max_f32_e32 v94, v94, v99
	v_max3_f32 v94, v94, v17, v1
	v_max3_f32 v94, v94, v18, v2
	v_max3_f32 v94, v94, v19, v3
	v_max3_f32 v94, v94, v20, v4
	v_max3_f32 v94, v94, v21, v5
	v_max3_f32 v94, v94, v22, v6
	v_max3_f32 v94, v94, v23, v7
	v_max3_f32 v94, v94, v24, v8
	v_max3_f32 v94, v94, v25, v9
	v_max3_f32 v94, v94, v26, v10
	v_max3_f32 v94, v94, v27, v11
	v_max3_f32 v94, v94, v28, v12
	v_max3_f32 v94, v94, v29, v13
	v_max3_f32 v94, v94, v30, v14
	v_max3_f32 v94, v94, v31, v15
	v_fmac_f32_e32 v98, 0x3e38aa3b, v94
	v_mbcnt_hi_u32_b32 v94, -1, v220
	v_and_b32_e32 v96, 64, v94
	v_xor_b32_e32 v95, 32, v94
	v_add_u32_e32 v96, 64, v96
	v_cmp_lt_i32_e32 vcc, v95, v96
	s_nop 1
	v_cndmask_b32_e32 v94, v94, v95, vcc
	v_lshlrev_b32_e32 v235, 2, v94
	ds_bpermute_b32 v94, v235, v98
	s_waitcnt lgkmcnt(0)
	v_max3_f32 v238, v98, v94, s2
	v_fma_f32 v110, v230, v64, -v238
	v_fmamk_f32 v0, v0, 0x3e38aa3b, v110
	v_sub_f32_e32 v94, 0xf149f2ca, v238
	v_fmamk_f32 v16, v16, 0x3e38aa3b, v110
	v_exp_f32_e32 v112, v0
	v_fmamk_f32 v0, v17, 0x3e38aa3b, v110
	v_exp_f32_e32 v94, v94
	v_exp_f32_e32 v111, v16
	v_exp_f32_e32 v64, v0
	v_fmamk_f32 v0, v1, 0x3e38aa3b, v110
	v_exp_f32_e32 v16, v0
	v_cmp_lt_f32_e32 vcc, s2, v238
	s_cmp_lg_u64 vcc, 0
	v_mul_f32_e32 v94, 0, v94
	s_cselect_b64 vcc, -1, 0
	v_add_f32_e32 v17, v112, v111
	v_cndmask_b32_e32 v0, 0, v94, vcc
	v_pk_add_f32 v[94:95], v[16:17], v[64:65]
	v_fmamk_f32 v2, v2, 0x3e38aa3b, v110
	v_pk_add_f32 v[96:97], v[94:95], v[94:95] op_sel_hi:[0,1]
	v_fmamk_f32 v17, v18, 0x3e38aa3b, v110
	v_exp_f32_e32 v113, v2
	v_fmamk_f32 v2, v19, 0x3e38aa3b, v110
	v_exp_f32_e32 v17, v17
	v_exp_f32_e32 v96, v2
	v_fmamk_f32 v2, v3, 0x3e38aa3b, v110
	v_exp_f32_e32 v18, v2
	v_add_f32_e32 v19, v113, v17
	v_fmamk_f32 v4, v4, 0x3e38aa3b, v110
	v_exp_f32_e32 v114, v4
	v_pk_add_f32 v[94:95], v[18:19], v[96:97]
	v_fmamk_f32 v19, v20, 0x3e38aa3b, v110
	v_pk_add_f32 v[98:99], v[94:95], v[94:95] op_sel_hi:[0,1]
	v_exp_f32_e32 v19, v19
	v_fmamk_f32 v4, v21, 0x3e38aa3b, v110
	v_fmamk_f32 v5, v5, 0x3e38aa3b, v110
	v_exp_f32_e32 v98, v4
	v_exp_f32_e32 v20, v5
	v_add_f32_e32 v21, v114, v19
	v_fmamk_f32 v6, v6, 0x3e38aa3b, v110
	v_exp_f32_e32 v115, v6
	v_pk_add_f32 v[94:95], v[20:21], v[98:99]
	v_fmamk_f32 v21, v22, 0x3e38aa3b, v110
	v_pk_add_f32 v[100:101], v[94:95], v[94:95] op_sel_hi:[0,1]
	v_fmamk_f32 v6, v23, 0x3e38aa3b, v110
	v_exp_f32_e32 v21, v21
	v_exp_f32_e32 v100, v6
	v_fmamk_f32 v6, v7, 0x3e38aa3b, v110
	v_exp_f32_e32 v22, v6
	v_add_f32_e32 v23, v115, v21
	v_fmamk_f32 v8, v8, 0x3e38aa3b, v110
	v_exp_f32_e32 v116, v8
	v_pk_add_f32 v[94:95], v[22:23], v[100:101]
	v_fmamk_f32 v23, v24, 0x3e38aa3b, v110
	v_pk_add_f32 v[102:103], v[94:95], v[94:95] op_sel_hi:[0,1]
	v_fmamk_f32 v8, v25, 0x3e38aa3b, v110
	v_exp_f32_e32 v23, v23
	v_exp_f32_e32 v102, v8
	v_fmamk_f32 v8, v9, 0x3e38aa3b, v110
	v_exp_f32_e32 v24, v8
	v_add_f32_e32 v25, v116, v23
	v_fmamk_f32 v10, v10, 0x3e38aa3b, v110
	v_exp_f32_e32 v117, v10
	v_pk_add_f32 v[94:95], v[24:25], v[102:103]
	v_fmamk_f32 v25, v26, 0x3e38aa3b, v110
	v_pk_add_f32 v[104:105], v[94:95], v[94:95] op_sel_hi:[0,1]
	v_fmamk_f32 v10, v27, 0x3e38aa3b, v110
	v_exp_f32_e32 v25, v25
	v_exp_f32_e32 v104, v10
	v_fmamk_f32 v10, v11, 0x3e38aa3b, v110
	v_exp_f32_e32 v26, v10
	v_add_f32_e32 v27, v117, v25
	v_fmamk_f32 v12, v12, 0x3e38aa3b, v110
	v_exp_f32_e32 v118, v12
	v_pk_add_f32 v[94:95], v[26:27], v[104:105]
	v_fmamk_f32 v27, v28, 0x3e38aa3b, v110
	v_pk_add_f32 v[106:107], v[94:95], v[94:95] op_sel_hi:[0,1]
	v_fmamk_f32 v12, v29, 0x3e38aa3b, v110
	v_exp_f32_e32 v27, v27
	v_exp_f32_e32 v106, v12
	v_fmamk_f32 v12, v13, 0x3e38aa3b, v110
	v_exp_f32_e32 v28, v12
; __device__ __forceinline__ unsigned pk2(float lo, float hi) { return pg8::cvt_pk_bf16(lo, hi); }
; #define SB_() __builtin_amdgcn_sched_barrier(0)
; __device__ __forceinline__ void tile_qk_fast(const KFr& f, const bf16x8 (&qf)[4], const bf16x8& kx0, const bf16x8& kx1, const bf16x8& qx, u32x4 (&pw)[4],
;                                              f32x16& o0, f32x16& o1, float& m, float& l, float off) {
;     ...
;     const float sh = off - mn;
;     float rs = 0.f;
; #pragma unroll
;     for (int r = 0; r < 16; ++r) { p0[r] = __builtin_amdgcn_exp2f(fmaf(p0[r], C2, sh)); p1[r] = __builtin_amdgcn_exp2f(fmaf(p1[r], C2, sh)); rs += p0[r] + p1[r]; }
;     l += rs;
;     pw[0] = (u32x4){pk2(p0[0], p0[1]), pk2(p0[2], p0[3]), pk2(p0[4], p0[5]), pk2(p0[6], p0[7])};
;     pw[1] = (u32x4){pk2(p0[8], p0[9]), pk2(p0[10], p0[11]), pk2(p0[12], p0[13]), pk2(p0[14], p0[15])};
;     pw[2] = (u32x4){pk2(p1[0], p1[1]), pk2(p1[2], p1[3]), pk2(p1[4], p1[5]), pk2(p1[6], p1[7])};
;     pw[3] = (u32x4){pk2(p1[8], p1[9]), pk2(p1[10], p1[11]), pk2(p1[12], p1[13]), pk2(p1[14], p1[15])};
; }
; __device__ __forceinline__ void tile_pv(const VFr& f, const u32x4 (&pw)[4], f32x16& o0, f32x16& o1) {
; #pragma unroll
;     for (int ks = 0; ks < 4; ++ks) {
;         const bf16x8 P = __builtin_bit_cast(bf16x8, pw[ks]);
;         o0 = __builtin_amdgcn_mfma_f32_32x32x16_bf16(f.a[0][ks], P, o0, 0, 0, 0);
;         o1 = __builtin_amdgcn_mfma_f32_32x32x16_bf16(f.a[1][ks], P, o1, 0, 0, 0);
; __device__ __forceinline__ void moba_unit(int b, int h, int qb, const bf16* qkv, const bf16* KF, const bf16* VF, bf16* Y, const float* kmean, LAS unsigned char* lds) {
;     ...
;             tile_pv(v0, pw, a0, a1); SB_();
;             loadV(v0, vp); loadK(k0, kp); SB_(); tile_qk_fast(k1, qg, kx0, kx1, qx, pw, a0, a1, m2, l2, sl2 * (float)(kq0 + 64)); SB_();
	v_add_f32_e32 v29, v118, v27
	v_fmamk_f32 v14, v14, 0x3e38aa3b, v110
	v_exp_f32_e32 v119, v14
	v_pk_add_f32 v[94:95], v[28:29], v[106:107]
	v_fmamk_f32 v29, v30, 0x3e38aa3b, v110
	v_pk_add_f32 v[108:109], v[94:95], v[94:95] op_sel_hi:[0,1]
	v_exp_f32_e32 v29, v29
	v_fmamk_f32 v14, v31, 0x3e38aa3b, v110
	v_fmac_f32_e32 v110, 0x3e38aa3b, v15
	v_exp_f32_e32 v108, v14
	v_exp_f32_e32 v30, v110
	v_add_f32_e32 v31, v119, v29
	v_mov_b32_e32 v1, v0
	v_mov_b32_e32 v2, v0
	v_pk_add_f32 v[94:95], v[30:31], v[108:109]
	v_mov_b32_e32 v3, v0
	v_add_f32_e32 v31, v94, v95
	v_mov_b32_e32 v4, v0
	v_mov_b32_e32 v5, v0
	v_mov_b32_e32 v6, v0
	v_mov_b32_e32 v7, v0
	v_mov_b32_e32 v8, v0
	v_mov_b32_e32 v9, v0
	v_mov_b32_e32 v10, v0
	v_mov_b32_e32 v11, v0
	v_mov_b32_e32 v12, v0
	v_mov_b32_e32 v13, v0
	v_mov_b32_e32 v14, v0
	v_mov_b32_e32 v15, v0
	v_add_f32_e32 v237, v0, v31
	v_cvt_pk_bf16_f32 v94, v111, v64
	v_cvt_pk_bf16_f32 v95, v17, v96
	v_cvt_pk_bf16_f32 v96, v19, v98
	v_cvt_pk_bf16_f32 v97, v21, v100
	v_cvt_pk_bf16_f32 v98, v23, v102
	v_cvt_pk_bf16_f32 v99, v25, v104
	v_cvt_pk_bf16_f32 v100, v27, v106
	v_cvt_pk_bf16_f32 v101, v29, v108
	v_cvt_pk_bf16_f32 v102, v112, v16
	v_cvt_pk_bf16_f32 v103, v113, v18
	v_cvt_pk_bf16_f32 v104, v114, v20
	v_cvt_pk_bf16_f32 v105, v115, v22
	v_cvt_pk_bf16_f32 v106, v116, v24
	v_cvt_pk_bf16_f32 v107, v117, v26
	v_cvt_pk_bf16_f32 v108, v118, v28
	v_cvt_pk_bf16_f32 v109, v119, v30
	s_waitcnt vmcnt(0)
	v_mfma_f32_32x32x16_bf16 v[16:31], v[162:165], v[94:97], v[0:15]
	v_mfma_f32_32x32x16_bf16 v[0:15], v[170:173], v[94:97], v[0:15]
	v_mfma_f32_32x32x16_bf16 v[16:31], v[154:157], v[98:101], v[16:31]
	v_mfma_f32_32x32x16_bf16 v[0:15], v[166:169], v[98:101], v[0:15]
	v_mfma_f32_32x32x16_bf16 v[16:31], v[146:149], v[102:105], v[16:31]
	v_mfma_f32_32x32x16_bf16 v[0:15], v[158:161], v[102:105], v[0:15]
	v_mfma_f32_32x32x16_bf16 v[16:31], v[142:145], v[106:109], v[16:31]
	v_mfma_f32_32x32x16_bf16 v[0:15], v[150:153], v[106:109], v[0:15]
	v_lshl_add_u64 v[94:95], v[216:217], 0, s[56:57]
	global_load_dwordx4 v[162:165], v[216:217], off
	global_load_dwordx4 v[154:157], v[216:217], off offset:1024
	global_load_dwordx4 v[146:149], v[216:217], off offset:2048
	global_load_dwordx4 v[142:145], v[216:217], off offset:3072
	v_lshl_add_u64 v[216:217], v[218:219], 0, s[56:57]
	v_lshl_add_u64 v[214:215], v[94:95], 0, s[56:57]
	global_load_dwordx4 v[170:173], v[94:95], off
	global_load_dwordx4 v[166:169], v[94:95], off offset:1024
	global_load_dwordx4 v[158:161], v[94:95], off offset:2048
	global_load_dwordx4 v[150:153], v[94:95], off offset:3072
	global_load_dwordx4 v[106:109], v[218:219], off
	global_load_dwordx4 v[102:105], v[218:219], off offset:1024
	global_load_dwordx4 v[98:101], v[218:219], off offset:2048
	global_load_dwordx4 v[94:97], v[218:219], off offset:3072
	global_load_dwordx4 v[122:125], v[216:217], off
	global_load_dwordx4 v[118:121], v[216:217], off offset:1024
	global_load_dwordx4 v[114:117], v[216:217], off offset:2048
	global_load_dwordx4 v[110:113], v[216:217], off offset:3072
	v_lshl_add_u64 v[216:217], v[216:217], 0, s[56:57]
	v_mfma_f32_32x32x16_bf16 v[48:63], v[194:197], v[138:141], v[48:63]
	v_add_u32_e32 v64, 64, v236
	v_cvt_f32_i32_e32 v64, v64
	v_mul_f32_e32 v64, v230, v64
	v_mfma_f32_32x32x16_bf16 v[32:47], v[202:205], v[138:141], v[32:47]
	v_mfma_f32_32x32x16_bf16 v[48:63], v[186:189], v[134:137], v[48:63]
	v_mfma_f32_32x32x16_bf16 v[32:47], v[198:201], v[134:137], v[32:47]
	v_mfma_f32_32x32x16_bf16 v[48:63], v[182:185], v[130:133], v[48:63]
	v_mfma_f32_32x32x16_bf16 v[32:47], v[190:193], v[130:133], v[32:47]
	v_mfma_f32_32x32x16_bf16 v[48:63], v[174:177], v[126:129], v[48:63]
	v_mfma_f32_32x32x16_bf16 v[32:47], v[178:181], v[126:129], v[32:47]
	s_nop 10
	v_max_f32_e32 v174, v48, v48
	v_max_f32_e32 v175, v32, v32
	v_max_f32_e32 v174, v174, v175
	v_max3_f32 v174, v174, v49, v33
	v_max3_f32 v174, v174, v50, v34
	v_max3_f32 v174, v174, v51, v35
	v_max3_f32 v174, v174, v52, v36
	v_max3_f32 v174, v174, v53, v37
	v_max3_f32 v174, v174, v54, v38
	v_max3_f32 v174, v174, v55, v39
	v_max3_f32 v174, v174, v56, v40
	v_max3_f32 v174, v174, v57, v41
	v_max3_f32 v174, v174, v58, v42
	v_max3_f32 v174, v174, v59, v43
	v_max3_f32 v174, v174, v60, v44
	v_max3_f32 v174, v174, v61, v45
	v_max3_f32 v174, v174, v62, v46
	v_max3_f32 v174, v174, v63, v47
	v_fmamk_f32 v174, v174, 0x3e38aa3b, v64
	ds_bpermute_b32 v175, v235, v174
	s_waitcnt lgkmcnt(0)
	v_max3_f32 v213, v238, v174, v175
	v_cmp_gt_f32_e32 vcc, v213, v238
	s_cbranch_vccz .LBB0_256
	v_sub_f32_e32 v174, v238, v213
	v_exp_f32_e32 v174, v174
	s_nop 0
	v_mul_f32_e32 v237, v237, v174
	v_pk_mul_f32 v[30:31], v[30:31], v[174:175] op_sel_hi:[1,0]
	v_pk_mul_f32 v[28:29], v[28:29], v[174:175] op_sel_hi:[1,0]
	v_pk_mul_f32 v[26:27], v[26:27], v[174:175] op_sel_hi:[1,0]
	v_pk_mul_f32 v[24:25], v[24:25], v[174:175] op_sel_hi:[1,0]
	v_pk_mul_f32 v[22:23], v[22:23], v[174:175] op_sel_hi:[1,0]
	v_pk_mul_f32 v[20:21], v[20:21], v[174:175] op_sel_hi:[1,0]
	v_pk_mul_f32 v[18:19], v[18:19], v[174:175] op_sel_hi:[1,0]
	v_pk_mul_f32 v[16:17], v[16:17], v[174:175] op_sel_hi:[1,0]
	v_pk_mul_f32 v[14:15], v[14:15], v[174:175] op_sel_hi:[1,0]
	v_pk_mul_f32 v[12:13], v[12:13], v[174:175] op_sel_hi:[1,0]
	v_pk_mul_f32 v[10:11], v[10:11], v[174:175] op_sel_hi:[1,0]
	v_pk_mul_f32 v[8:9], v[8:9], v[174:175] op_sel_hi:[1,0]
	v_pk_mul_f32 v[6:7], v[6:7], v[174:175] op_sel_hi:[1,0]
	v_pk_mul_f32 v[4:5], v[4:5], v[174:175] op_sel_hi:[1,0]
	v_pk_mul_f32 v[2:3], v[2:3], v[174:175] op_sel_hi:[1,0]
	v_pk_mul_f32 v[0:1], v[0:1], v[174:175] op_sel_hi:[1,0]
; __device__ __forceinline__ unsigned pk2(float lo, float hi) { return pg8::cvt_pk_bf16(lo, hi); }
; #define SB_() __builtin_amdgcn_sched_barrier(0)
; __device__ __forceinline__ void tile_qk_fast(const KFr& f, const bf16x8 (&qf)[4], const bf16x8& kx0, const bf16x8& kx1, const bf16x8& qx, u32x4 (&pw)[4],
;                                              f32x16& o0, f32x16& o1, float& m, float& l, float off) {
;     ...
;     if (__ballot(mn > m) != 0ull) {
;         const float alpha = __builtin_amdgcn_exp2f(m - mn); l *= alpha;
; #pragma unroll
;         for (int r = 0; r < 16; ++r) { o0[r] *= alpha; o1[r] *= alpha; }
;     }
;     m = mn;
;     const float sh = off - mn;
;     float rs = 0.f;
; #pragma unroll
;     for (int r = 0; r < 16; ++r) { p0[r] = __builtin_amdgcn_exp2f(fmaf(p0[r], C2, sh)); p1[r] = __builtin_amdgcn_exp2f(fmaf(p1[r], C2, sh)); rs += p0[r] + p1[r]; }
;     l += rs;
;     pw[0] = (u32x4){pk2(p0[0], p0[1]), pk2(p0[2], p0[3]), pk2(p0[4], p0[5]), pk2(p0[6], p0[7])};
;     pw[1] = (u32x4){pk2(p0[8], p0[9]), pk2(p0[10], p0[11]), pk2(p0[12], p0[13]), pk2(p0[14], p0[15])};
;     pw[2] = (u32x4){pk2(p1[0], p1[1]), pk2(p1[2], p1[3]), pk2(p1[4], p1[5]), pk2(p1[6], p1[7])};
;     pw[3] = (u32x4){pk2(p1[8], p1[9]), pk2(p1[10], p1[11]), pk2(p1[12], p1[13]), pk2(p1[14], p1[15])};
; }
; __device__ __forceinline__ void tile_pv(const VFr& f, const u32x4 (&pw)[4], f32x16& o0, f32x16& o1) {
; #pragma unroll
;     for (int ks = 0; ks < 4; ++ks) {
;         const bf16x8 P = __builtin_bit_cast(bf16x8, pw[ks]);
;         o0 = __builtin_amdgcn_mfma_f32_32x32x16_bf16(f.a[0][ks], P, o0, 0, 0, 0);
;         o1 = __builtin_amdgcn_mfma_f32_32x32x16_bf16(f.a[1][ks], P, o1, 0, 0, 0);
; __device__ __forceinline__ void moba_unit(int b, int h, int qb, const bf16* qkv, const bf16* KF, const bf16* VF, bf16* Y, const float* kmean, LAS unsigned char* lds) {
;     ...
;             loadV(v0, vp); loadK(k0, kp); SB_(); tile_qk_fast(k1, qg, kx0, kx1, qx, pw, a0, a1, m2, l2, sl2 * (float)(kq0 + 64)); SB_();
;             tile_pv(v0, pw, a0, a1); SB_();
;             loadV(v0, vp); loadK(k1, kp); SB_(); tile_qk_fast(k0, qg, kx0, kx1, qx, pw, a0, a1, m2, l2, sl2 * (float)(kq0 + 128)); SB_();
.LBB0_256:
	v_sub_f32_e32 v176, v64, v213
	v_fmamk_f32 v32, v32, 0x3e38aa3b, v176
	v_fmamk_f32 v48, v48, 0x3e38aa3b, v176
	v_exp_f32_e32 v178, v32
	v_fmamk_f32 v32, v49, 0x3e38aa3b, v176
	v_exp_f32_e32 v177, v48
	v_exp_f32_e32 v64, v32
	v_fmamk_f32 v32, v33, 0x3e38aa3b, v176
	v_exp_f32_e32 v48, v32
	v_add_f32_e32 v49, v178, v177
	v_pk_add_f32 v[32:33], v[48:49], v[64:65]
	s_nop 0
	v_pk_add_f32 v[174:175], v[32:33], v[32:33] op_sel_hi:[0,1]
	v_fmamk_f32 v32, v50, 0x3e38aa3b, v176
	v_exp_f32_e32 v49, v32
	v_fmamk_f32 v32, v34, 0x3e38aa3b, v176
	v_exp_f32_e32 v179, v32
	v_fmamk_f32 v32, v51, 0x3e38aa3b, v176
	v_exp_f32_e32 v174, v32
	v_fmamk_f32 v32, v35, 0x3e38aa3b, v176
	v_exp_f32_e32 v50, v32
	v_add_f32_e32 v51, v179, v49
	v_pk_add_f32 v[32:33], v[50:51], v[174:175]
	s_nop 0
	v_pk_add_f32 v[34:35], v[32:33], v[32:33] op_sel_hi:[0,1]
	v_fmamk_f32 v32, v52, 0x3e38aa3b, v176
	v_exp_f32_e32 v51, v32
	v_fmamk_f32 v32, v36, 0x3e38aa3b, v176
	v_exp_f32_e32 v175, v32
	v_fmamk_f32 v32, v53, 0x3e38aa3b, v176
	v_exp_f32_e32 v34, v32
	v_fmamk_f32 v32, v37, 0x3e38aa3b, v176
	v_exp_f32_e32 v52, v32
	v_add_f32_e32 v53, v175, v51
	v_pk_add_f32 v[32:33], v[52:53], v[34:35]
	s_nop 0
	v_pk_add_f32 v[36:37], v[32:33], v[32:33] op_sel_hi:[0,1]
	v_fmamk_f32 v32, v54, 0x3e38aa3b, v176
	v_exp_f32_e32 v35, v32
	v_fmamk_f32 v32, v38, 0x3e38aa3b, v176
	v_exp_f32_e32 v53, v32
	v_fmamk_f32 v32, v55, 0x3e38aa3b, v176
	v_exp_f32_e32 v36, v32
	v_fmamk_f32 v32, v39, 0x3e38aa3b, v176
	v_exp_f32_e32 v54, v32
	v_add_f32_e32 v55, v53, v35
	v_cvt_pk_bf16_f32 v34, v51, v34
	v_cvt_pk_bf16_f32 v35, v35, v36
	v_pk_add_f32 v[32:33], v[54:55], v[36:37]
	s_nop 0
	v_pk_add_f32 v[38:39], v[32:33], v[32:33] op_sel_hi:[0,1]
	v_fmamk_f32 v32, v56, 0x3e38aa3b, v176
	v_exp_f32_e32 v37, v32
	v_fmamk_f32 v32, v40, 0x3e38aa3b, v176
	v_exp_f32_e32 v55, v32
	v_fmamk_f32 v32, v57, 0x3e38aa3b, v176
	v_exp_f32_e32 v38, v32
	v_fmamk_f32 v32, v41, 0x3e38aa3b, v176
	v_exp_f32_e32 v56, v32
	v_add_f32_e32 v57, v55, v37
	v_cvt_pk_bf16_f32 v36, v37, v38
	v_pk_add_f32 v[32:33], v[56:57], v[38:39]
	s_nop 0
	v_pk_add_f32 v[40:41], v[32:33], v[32:33] op_sel_hi:[0,1]
	v_fmamk_f32 v32, v58, 0x3e38aa3b, v176
	v_exp_f32_e32 v39, v32
	v_fmamk_f32 v32, v42, 0x3e38aa3b, v176
	v_exp_f32_e32 v57, v32
	v_fmamk_f32 v32, v59, 0x3e38aa3b, v176
	v_exp_f32_e32 v40, v32
	v_fmamk_f32 v32, v43, 0x3e38aa3b, v176
	v_exp_f32_e32 v58, v32
	v_add_f32_e32 v59, v57, v39
	v_cvt_pk_bf16_f32 v37, v39, v40
	v_pk_add_f32 v[32:33], v[58:59], v[40:41]
	s_nop 0
	v_pk_add_f32 v[42:43], v[32:33], v[32:33] op_sel_hi:[0,1]
	v_fmamk_f32 v32, v60, 0x3e38aa3b, v176
	v_exp_f32_e32 v41, v32
	v_fmamk_f32 v32, v44, 0x3e38aa3b, v176
	v_exp_f32_e32 v59, v32
	v_fmamk_f32 v32, v61, 0x3e38aa3b, v176
	v_exp_f32_e32 v42, v32
	v_fmamk_f32 v32, v45, 0x3e38aa3b, v176
	v_exp_f32_e32 v60, v32
	v_add_f32_e32 v61, v59, v41
	v_cvt_pk_bf16_f32 v38, v41, v42
	v_cvt_pk_bf16_f32 v40, v178, v48
	v_pk_add_f32 v[32:33], v[60:61], v[42:43]
	v_cvt_pk_bf16_f32 v41, v179, v50
	v_pk_add_f32 v[44:45], v[32:33], v[32:33] op_sel_hi:[0,1]
	v_fmamk_f32 v32, v62, 0x3e38aa3b, v176
	v_exp_f32_e32 v43, v32
	v_fmamk_f32 v32, v46, 0x3e38aa3b, v176
	v_exp_f32_e32 v61, v32
	v_fmamk_f32 v32, v63, 0x3e38aa3b, v176
	v_fmac_f32_e32 v176, 0x3e38aa3b, v47
	v_exp_f32_e32 v44, v32
	v_exp_f32_e32 v62, v176
	v_add_f32_e32 v63, v61, v43
	v_cvt_pk_bf16_f32 v42, v175, v52
	v_cvt_pk_bf16_f32 v39, v43, v44
	v_pk_add_f32 v[32:33], v[62:63], v[44:45]
	v_cvt_pk_bf16_f32 v43, v53, v54
	v_add_f32_e32 v32, v32, v33
	v_add_f32_e32 v237, v32, v237
	v_cvt_pk_bf16_f32 v32, v177, v64
	v_cvt_pk_bf16_f32 v33, v49, v174
	v_cvt_pk_bf16_f32 v44, v55, v56
	v_cvt_pk_bf16_f32 v45, v57, v58
	v_cvt_pk_bf16_f32 v46, v59, v60
	v_cvt_pk_bf16_f32 v47, v61, v62
	s_waitcnt vmcnt(0)
	v_mfma_f32_32x32x16_bf16 v[16:31], v[162:165], v[32:35], v[16:31]
	v_mfma_f32_32x32x16_bf16 v[0:15], v[170:173], v[32:35], v[0:15]
	v_mfma_f32_32x32x16_bf16 v[16:31], v[154:157], v[36:39], v[16:31]
	v_mfma_f32_32x32x16_bf16 v[0:15], v[166:169], v[36:39], v[0:15]
	v_mfma_f32_32x32x16_bf16 v[16:31], v[146:149], v[40:43], v[16:31]
	v_mfma_f32_32x32x16_bf16 v[0:15], v[158:161], v[40:43], v[0:15]
	v_mfma_f32_32x32x16_bf16 v[16:31], v[142:145], v[44:47], v[16:31]
	v_mfma_f32_32x32x16_bf16 v[0:15], v[150:153], v[44:47], v[0:15]
	v_lshl_add_u64 v[32:33], v[214:215], 0, s[56:57]
	global_load_dwordx4 v[162:165], v[214:215], off
	global_load_dwordx4 v[154:157], v[214:215], off offset:1024
	global_load_dwordx4 v[146:149], v[214:215], off offset:2048
	global_load_dwordx4 v[142:145], v[214:215], off offset:3072
	global_load_dwordx4 v[174:177], v[32:33], off
	global_load_dwordx4 v[166:169], v[32:33], off offset:1024
	global_load_dwordx4 v[158:161], v[32:33], off offset:2048
	global_load_dwordx4 v[150:153], v[32:33], off offset:3072
	v_lshl_add_u64 v[218:219], v[32:33], 0, s[56:57]
	v_lshl_add_u64 v[32:33], v[216:217], 0, s[56:57]
	global_load_dwordx4 v[194:197], v[216:217], off
	global_load_dwordx4 v[186:189], v[216:217], off offset:1024
	global_load_dwordx4 v[178:181], v[216:217], off offset:2048
	global_load_dwordx4 v[170:173], v[216:217], off offset:3072
	global_load_dwordx4 v[202:205], v[32:33], off
	global_load_dwordx4 v[198:201], v[32:33], off offset:1024
	global_load_dwordx4 v[190:193], v[32:33], off offset:2048
	global_load_dwordx4 v[182:185], v[32:33], off offset:3072
	v_lshl_add_u64 v[214:215], v[32:33], 0, s[56:57]
	v_mfma_f32_32x32x16_bf16 v[48:63], v[70:73], v[66:69], 0
	v_add_u32_e32 v64, 0x80, v236
	v_cvt_f32_i32_e32 v64, v64
	v_mul_f32_e32 v216, v230, v64
	v_mfma_f32_32x32x16_bf16 v[32:47], v[74:77], v[66:69], 0
	v_mfma_f32_32x32x16_bf16 v[48:63], v[106:109], v[138:141], v[48:63]
	v_mfma_f32_32x32x16_bf16 v[32:47], v[122:125], v[138:141], v[32:47]
	v_mfma_f32_32x32x16_bf16 v[48:63], v[102:105], v[134:137], v[48:63]
	v_mfma_f32_32x32x16_bf16 v[32:47], v[118:121], v[134:137], v[32:47]
	v_mfma_f32_32x32x16_bf16 v[48:63], v[98:101], v[130:133], v[48:63]
	v_mfma_f32_32x32x16_bf16 v[32:47], v[114:117], v[130:133], v[32:47]
	v_mfma_f32_32x32x16_bf16 v[32:47], v[110:113], v[126:129], v[32:47]
	v_mfma_f32_32x32x16_bf16 v[48:63], v[94:97], v[126:129], v[48:63]
	s_nop 10
	v_max_f32_e32 v64, v32, v32
	v_max_f32_e32 v217, v48, v48
	v_max_f32_e32 v64, v217, v64
	v_max3_f32 v64, v64, v49, v33
	v_max3_f32 v64, v64, v50, v34
	v_max3_f32 v64, v64, v51, v35
	v_max3_f32 v64, v64, v52, v36
	v_max3_f32 v64, v64, v53, v37
	v_max3_f32 v64, v64, v54, v38
	v_max3_f32 v64, v64, v55, v39
	v_max3_f32 v64, v64, v56, v40
	v_max3_f32 v64, v64, v57, v41
	v_max3_f32 v64, v64, v58, v42
	v_max3_f32 v64, v64, v59, v43
	v_max3_f32 v64, v64, v60, v44
	v_max3_f32 v64, v64, v61, v45
	v_max3_f32 v64, v64, v62, v46
	v_max3_f32 v64, v64, v63, v47
	v_fmamk_f32 v64, v64, 0x3e38aa3b, v216
	ds_bpermute_b32 v217, v235, v64
	s_waitcnt lgkmcnt(0)
	v_max3_f32 v64, v213, v64, v217
	v_cmp_gt_f32_e32 vcc, v64, v213
	s_cbranch_vccz .LBB0_258
; __device__ __forceinline__ unsigned pk2(float lo, float hi) { return pg8::cvt_pk_bf16(lo, hi); }
; #define SB_() __builtin_amdgcn_sched_barrier(0)
; __device__ __forceinline__ void tile_qk_fast(const KFr& f, const bf16x8 (&qf)[4], const bf16x8& kx0, const bf16x8& kx1, const bf16x8& qx, u32x4 (&pw)[4],
;                                              f32x16& o0, f32x16& o1, float& m, float& l, float off) {
;     ...
;     if (__ballot(mn > m) != 0ull) {
;         const float alpha = __builtin_amdgcn_exp2f(m - mn); l *= alpha;
; #pragma unroll
;         for (int r = 0; r < 16; ++r) { o0[r] *= alpha; o1[r] *= alpha; }
;     }
;     m = mn;
;     const float sh = off - mn;
;     float rs = 0.f;
; #pragma unroll
;     for (int r = 0; r < 16; ++r) { p0[r] = __builtin_amdgcn_exp2f(fmaf(p0[r], C2, sh)); p1[r] = __builtin_amdgcn_exp2f(fmaf(p1[r], C2, sh)); rs += p0[r] + p1[r]; }
;     l += rs;
;     pw[0] = (u32x4){pk2(p0[0], p0[1]), pk2(p0[2], p0[3]), pk2(p0[4], p0[5]), pk2(p0[6], p0[7])};
;     pw[1] = (u32x4){pk2(p0[8], p0[9]), pk2(p0[10], p0[11]), pk2(p0[12], p0[13]), pk2(p0[14], p0[15])};
;     pw[2] = (u32x4){pk2(p1[0], p1[1]), pk2(p1[2], p1[3]), pk2(p1[4], p1[5]), pk2(p1[6], p1[7])};
;     pw[3] = (u32x4){pk2(p1[8], p1[9]), pk2(p1[10], p1[11]), pk2(p1[12], p1[13]), pk2(p1[14], p1[15])};
; }
; __device__ __forceinline__ void tile_pv(const VFr& f, const u32x4 (&pw)[4], f32x16& o0, f32x16& o1) {
; #pragma unroll
;     for (int ks = 0; ks < 4; ++ks) {
;         const bf16x8 P = __builtin_bit_cast(bf16x8, pw[ks]);
;         o0 = __builtin_amdgcn_mfma_f32_32x32x16_bf16(f.a[0][ks], P, o0, 0, 0, 0);
;         o1 = __builtin_amdgcn_mfma_f32_32x32x16_bf16(f.a[1][ks], P, o1, 0, 0, 0);
; __device__ __forceinline__ void moba_unit(int b, int h, int qb, const bf16* qkv, const bf16* KF, const bf16* VF, bf16* Y, const float* kmean, LAS unsigned char* lds) {
;     ...
;             loadV(v0, vp); loadK(k1, kp); SB_(); tile_qk_fast(k0, qg, kx0, kx1, qx, pw, a0, a1, m2, l2, sl2 * (float)(kq0 + 128)); SB_();
;             tile_pv(v0, pw, a0, a1); SB_();
;             bf16x8 qn[4]; int q2n = 0; bool validn = false;
;             loadV(v0, vp);
;             if (have) { TASK_Q(q2n, validn, qn); kp = (const char*)KFh + (size_t)(4 * n) * 8192 + lane * 16; asm volatile("" : "+v"(kp)); loadK(k0, kp); }
	v_sub_f32_e32 v213, v213, v64
	v_exp_f32_e32 v222, v213
	s_nop 0
	v_mul_f32_e32 v237, v237, v222
	v_pk_mul_f32 v[30:31], v[30:31], v[222:223] op_sel_hi:[1,0]
	v_pk_mul_f32 v[28:29], v[28:29], v[222:223] op_sel_hi:[1,0]
	v_pk_mul_f32 v[26:27], v[26:27], v[222:223] op_sel_hi:[1,0]
	v_pk_mul_f32 v[24:25], v[24:25], v[222:223] op_sel_hi:[1,0]
	v_pk_mul_f32 v[22:23], v[22:23], v[222:223] op_sel_hi:[1,0]
	v_pk_mul_f32 v[20:21], v[20:21], v[222:223] op_sel_hi:[1,0]
	v_pk_mul_f32 v[18:19], v[18:19], v[222:223] op_sel_hi:[1,0]
	v_pk_mul_f32 v[16:17], v[16:17], v[222:223] op_sel_hi:[1,0]
	v_pk_mul_f32 v[14:15], v[14:15], v[222:223] op_sel_hi:[1,0]
	v_pk_mul_f32 v[12:13], v[12:13], v[222:223] op_sel_hi:[1,0]
	v_pk_mul_f32 v[10:11], v[10:11], v[222:223] op_sel_hi:[1,0]
	v_pk_mul_f32 v[8:9], v[8:9], v[222:223] op_sel_hi:[1,0]
	v_pk_mul_f32 v[6:7], v[6:7], v[222:223] op_sel_hi:[1,0]
	v_pk_mul_f32 v[4:5], v[4:5], v[222:223] op_sel_hi:[1,0]
	v_pk_mul_f32 v[2:3], v[2:3], v[222:223] op_sel_hi:[1,0]
	v_pk_mul_f32 v[0:1], v[0:1], v[222:223] op_sel_hi:[1,0]
.LBB0_258:
	v_sub_f32_e32 v213, v216, v64
	v_fmamk_f32 v48, v48, 0x3e38aa3b, v213
	v_fmamk_f32 v32, v32, 0x3e38aa3b, v213
	v_fmamk_f32 v49, v49, 0x3e38aa3b, v213
	v_fmamk_f32 v33, v33, 0x3e38aa3b, v213
	v_fmamk_f32 v50, v50, 0x3e38aa3b, v213
	v_fmamk_f32 v34, v34, 0x3e38aa3b, v213
	v_fmamk_f32 v51, v51, 0x3e38aa3b, v213
	v_fmamk_f32 v35, v35, 0x3e38aa3b, v213
	v_fmamk_f32 v52, v52, 0x3e38aa3b, v213
	v_fmamk_f32 v36, v36, 0x3e38aa3b, v213
	v_fmamk_f32 v53, v53, 0x3e38aa3b, v213
	v_fmamk_f32 v37, v37, 0x3e38aa3b, v213
	v_fmamk_f32 v54, v54, 0x3e38aa3b, v213
	v_fmamk_f32 v38, v38, 0x3e38aa3b, v213
	v_fmamk_f32 v55, v55, 0x3e38aa3b, v213
	v_fmamk_f32 v39, v39, 0x3e38aa3b, v213
	v_fmamk_f32 v56, v56, 0x3e38aa3b, v213
	v_fmamk_f32 v40, v40, 0x3e38aa3b, v213
	v_fmamk_f32 v57, v57, 0x3e38aa3b, v213
	v_fmamk_f32 v41, v41, 0x3e38aa3b, v213
	v_fmamk_f32 v58, v58, 0x3e38aa3b, v213
	v_fmamk_f32 v42, v42, 0x3e38aa3b, v213
	v_fmamk_f32 v59, v59, 0x3e38aa3b, v213
	v_fmamk_f32 v43, v43, 0x3e38aa3b, v213
	v_fmamk_f32 v60, v60, 0x3e38aa3b, v213
	v_fmamk_f32 v44, v44, 0x3e38aa3b, v213
	v_fmamk_f32 v61, v61, 0x3e38aa3b, v213
	v_fmamk_f32 v45, v45, 0x3e38aa3b, v213
	v_fmamk_f32 v62, v62, 0x3e38aa3b, v213
	v_fmamk_f32 v46, v46, 0x3e38aa3b, v213
	v_fmamk_f32 v63, v63, 0x3e38aa3b, v213
	v_fmac_f32_e32 v213, 0x3e38aa3b, v47
	v_exp_f32_e32 v48, v48
	v_exp_f32_e32 v32, v32
	v_exp_f32_e32 v49, v49
	v_exp_f32_e32 v33, v33
	v_exp_f32_e32 v50, v50
	v_exp_f32_e32 v34, v34
	v_exp_f32_e32 v51, v51
	v_exp_f32_e32 v35, v35
	v_exp_f32_e32 v52, v52
	v_exp_f32_e32 v36, v36
	v_exp_f32_e32 v53, v53
	v_exp_f32_e32 v37, v37
	v_exp_f32_e32 v54, v54
	v_exp_f32_e32 v38, v38
	v_exp_f32_e32 v55, v55
	v_exp_f32_e32 v39, v39
	v_exp_f32_e32 v56, v56
	v_exp_f32_e32 v40, v40
	v_exp_f32_e32 v57, v57
	v_exp_f32_e32 v41, v41
	v_exp_f32_e32 v58, v58
	v_exp_f32_e32 v42, v42
	v_exp_f32_e32 v59, v59
	v_exp_f32_e32 v43, v43
	v_exp_f32_e32 v60, v60
	v_exp_f32_e32 v44, v44
	v_exp_f32_e32 v61, v61
	v_exp_f32_e32 v45, v45
	v_exp_f32_e32 v62, v62
	v_exp_f32_e32 v46, v46
	v_exp_f32_e32 v63, v63
	v_exp_f32_e32 v47, v213
	v_cvt_pk_bf16_f32 v238, v48, v49
	v_cvt_pk_bf16_f32 v239, v50, v51
	v_cvt_pk_bf16_f32 v240, v52, v53
	v_cvt_pk_bf16_f32 v241, v54, v55
	v_cvt_pk_bf16_f32 v242, v56, v57
	v_cvt_pk_bf16_f32 v243, v58, v59
	v_cvt_pk_bf16_f32 v244, v60, v61
	v_cvt_pk_bf16_f32 v245, v62, v63
	v_cvt_pk_bf16_f32 v246, v32, v33
	v_cvt_pk_bf16_f32 v247, v34, v35
	v_cvt_pk_bf16_f32 v248, v36, v37
	v_cvt_pk_bf16_f32 v249, v38, v39
	v_cvt_pk_bf16_f32 v222, v40, v41
	v_cvt_pk_bf16_f32 v223, v42, v43
	v_cvt_pk_bf16_f32 v224, v44, v45
	v_cvt_pk_bf16_f32 v225, v46, v47
	s_waitcnt vmcnt(0)
	v_mfma_f32_32x32x16_bf16 v[16:31], v[162:165], v[238:241], v[16:31]
	v_mfma_f32_32x32x16_bf16 v[0:15], v[174:177], v[238:241], v[0:15]
	v_mfma_f32_32x32x16_bf16 v[16:31], v[154:157], v[242:245], v[16:31]
	v_mfma_f32_32x32x16_bf16 v[0:15], v[166:169], v[242:245], v[0:15]
	v_mfma_f32_32x32x16_bf16 v[16:31], v[146:149], v[246:249], v[16:31]
	v_mfma_f32_32x32x16_bf16 v[0:15], v[158:161], v[246:249], v[0:15]
	v_mfma_f32_32x32x16_bf16 v[16:31], v[142:145], v[222:225], v[16:31]
	v_mfma_f32_32x32x16_bf16 v[0:15], v[150:153], v[222:225], v[0:15]
	v_lshl_add_u64 v[216:217], v[218:219], 0, s[56:57]
	global_load_dwordx4 v[162:165], v[218:219], off
	global_load_dwordx4 v[154:157], v[218:219], off offset:1024
	global_load_dwordx4 v[146:149], v[218:219], off offset:2048
	global_load_dwordx4 v[142:145], v[218:219], off offset:3072
	global_load_dwordx4 v[174:177], v[216:217], off
	global_load_dwordx4 v[166:169], v[216:217], off offset:1024
	global_load_dwordx4 v[158:161], v[216:217], off offset:2048
	global_load_dwordx4 v[150:153], v[216:217], off offset:3072
	v_lshl_add_u64 v[216:217], v[216:217], 0, s[56:57]
	s_andn2_b64 vcc, exec, s[14:15]
	s_cbranch_vccnz .LBB0_260
	s_lshl_b32 s2, s25, 5
	v_or_b32_e32 v78, s2, v232
	s_lshl_b32 s3, s24, 8
	v_mov_b32_e32 v79, s2
	v_cmp_lt_i32_e32 vcc, v78, v231
	s_add_i32 s2, s3, 0
	v_readlane_b32 s16, v252, 59
	v_cndmask_b32_e32 v78, v79, v78, vcc
	v_add_u32_e32 v78, s2, v78
	v_add_u32_e32 v78, 0x1b000, v78
	ds_read_u8 v216, v78
	s_movk_i32 s2, 0x1e00
	v_readlane_b32 s17, v252, 60
	v_mov_b32_e32 v213, v65
	s_waitcnt lgkmcnt(0)
	v_or_b32_e32 v78, s21, v216
	v_or_b32_e32 v80, s16, v78
	v_mov_b64_e32 v[78:79], s[36:37]
	v_mad_u64_u32 v[78:79], s[2:3], v80, s2, v[78:79]
	v_mad_i32_i24 v79, s17, v226, v79
	v_lshl_add_u64 v[78:79], v[78:79], 0, s[46:47]
	v_lshl_add_u64 v[78:79], v[78:79], 0, v[212:213]
	s_mov_b64 s[2:3], 0x1200
	v_lshl_add_u64 v[90:91], v[78:79], 0, s[2:3]
	s_movk_i32 s2, 0x1000
	v_add_co_u32_e64 v86, s[2:3], s2, v78
	s_nop 1
	v_addc_co_u32_e64 v87, s[2:3], 0, v79, s[2:3]
	s_lshl_b32 s2, s24, 2
	s_ashr_i32 s3, s2, 31
	s_lshl_b64 s[2:3], s[2:3], 13
	v_lshl_add_u64 v[110:111], v[208:209], 0, s[2:3]
	global_load_dwordx4 v[78:81], v[90:91], off offset:32
	global_load_dwordx4 v[82:85], v[90:91], off offset:64
	s_nop 0
	global_load_dwordx4 v[86:89], v[86:87], off offset:512
	s_nop 0
	global_load_dwordx4 v[90:93], v[90:91], off offset:96
	global_load_dwordx4 v[106:109], v[110:111], off
	global_load_dwordx4 v[102:105], v[110:111], off offset:1024
	global_load_dwordx4 v[98:101], v[110:111], off offset:2048
	global_load_dwordx4 v[94:97], v[110:111], off offset:3072
	v_lshl_add_u64 v[214:215], v[110:111], 0, s[56:57]
	global_load_dwordx4 v[122:125], v[214:215], off
	global_load_dwordx4 v[118:121], v[214:215], off offset:1024
	global_load_dwordx4 v[114:117], v[214:215], off offset:2048
	global_load_dwordx4 v[110:113], v[214:215], off offset:3072
	v_lshl_add_u64 v[214:215], v[214:215], 0, s[56:57]
	s_and_b64 s[2:3], vcc, exec
	s_branch .LBB0_261

; template <int MASK>
; __device__ __forceinline__ void tile_qk(const KFr& f, const bf16x8 (&qf)[4], u32x4 (&pw)[4], f32x16& o0, f32x16& o1, float& m, float& l, int kq, float sl2, int lane) {
;     const int hi = lane >> 5;
;     f32x16 p0, p1;
; #pragma unroll
;     for (int r = 0; r < 16; ++r) { p0[r] = 0.f; p1[r] = 0.f; }
; #pragma unroll
;     for (int d0 = 0; d0 < 4; ++d0) {
;         p0 = __builtin_amdgcn_mfma_f32_32x32x16_bf16(f.a[0][d0], qf[d0], p0, 0, 0, 0);
;         p1 = __builtin_amdgcn_mfma_f32_32x32x16_bf16(f.a[1][d0], qf[d0], p1, 0, 0, 0);
;     }
;     constexpr float C2 = 0.125f * LOG2E;
;     const int dk0 = kq + 4 * hi;
;     float sl = sl2; asm volatile("" : "+v"(sl));
;     const float base = sl * (float)dk0;
;     const float NEG = -INFINITY;
;     float mx = NEG;
; #pragma unroll
;     for (int r = 0; r < 16; ++r) {
;         const int kk = (r & 3) + 8 * (r >> 2);
;         float t0 = fmaf(p0[r], C2, fmaf((float)kk, sl, base)), t1 = fmaf(p1[r], C2, fmaf((float)(kk + 32), sl, base));
;         if (MASK == 1) { if (dk0 + kk > 0) t0 = NEG; if (dk0 + kk + 32 > 0) t1 = NEG; }
;         p0[r] = t0; p1[r] = t1; mx = fmaxf(mx, fmaxf(t0, t1));
; __device__ __forceinline__ void moba_unit(int b, int h, int qb, const bf16* qkv, const bf16* KF, const bf16* VF, bf16* Y, const float* kmean, LAS unsigned char* lds) {
;     ...
;         for (int i = 0; i < nown; ++i) {
;             loadK(k0, kp); loadV(v0, vp);
;             tile_qk<1>(k0, qo, pw, o0, o1, m, l, 64 * i - qloc, sl2, lane); tile_pv(v0, pw, o0, o1);
.LBB0_268:
	v_lshl_add_u64 v[40:41], v[118:119], 0, s[56:57]
	v_mov_b32_e32 v124, v32
	global_load_dwordx4 v[32:35], v[118:119], off
	global_load_dwordx4 v[126:129], v[118:119], off offset:1024
	global_load_dwordx4 v[130:133], v[118:119], off offset:2048
	global_load_dwordx4 v[134:137], v[118:119], off offset:3072
	global_load_dwordx4 v[36:39], v[40:41], off
	global_load_dwordx4 v[138:141], v[40:41], off offset:1024
	global_load_dwordx4 v[142:145], v[40:41], off offset:2048
	global_load_dwordx4 v[146:149], v[40:41], off offset:3072
	v_lshl_add_u64 v[118:119], v[40:41], 0, s[56:57]
	v_lshl_add_u64 v[40:41], v[120:121], 0, s[56:57]
	v_mov_b32_e32 v123, v50
	global_load_dwordx4 v[94:97], v[120:121], off
	global_load_dwordx4 v[90:93], v[120:121], off offset:1024
	global_load_dwordx4 v[86:89], v[120:121], off offset:2048
	global_load_dwordx4 v[82:85], v[120:121], off offset:3072
	global_load_dwordx4 v[110:113], v[40:41], off
	global_load_dwordx4 v[106:109], v[40:41], off offset:1024
	global_load_dwordx4 v[102:105], v[40:41], off offset:2048
	global_load_dwordx4 v[98:101], v[40:41], off offset:3072
	v_lshl_add_u64 v[120:121], v[40:41], 0, s[56:57]
	v_cmp_gt_i32_e32 vcc, 1, v117
	s_add_i32 s0, s0, -1
	s_cmp_eq_u32 s0, 0
	s_waitcnt vmcnt(0) lgkmcnt(0)
	v_mfma_f32_32x32x16_bf16 v[48:63], v[32:35], v[78:81], 0
	v_mfma_f32_32x32x16_bf16 v[32:47], v[36:39], v[78:81], 0
	v_mfma_f32_32x32x16_bf16 v[48:63], v[126:129], v[70:73], v[48:63]
	v_cvt_f32_i32_e32 v126, v117
	v_mov_b32_e32 v129, v230
	v_mfma_f32_32x32x16_bf16 v[32:47], v[138:141], v[70:73], v[32:47]
	v_mfma_f32_32x32x16_bf16 v[48:63], v[130:133], v[66:69], v[48:63]
	v_mul_f32_e32 v130, v129, v126
	v_fma_f32 v125, 0, v129, v130
	v_fmamk_f32 v127, v129, 0x42000000, v130
	v_fma_f32 v126, v129, v126, v129
	v_fmamk_f32 v128, v129, 0x420c0000, v130
	v_mfma_f32_32x32x16_bf16 v[32:47], v[142:145], v[66:69], v[32:47]
	v_mfma_f32_32x32x16_bf16 v[48:63], v[134:137], v[74:77], v[48:63]
	v_mfma_f32_32x32x16_bf16 v[32:47], v[146:149], v[74:77], v[32:47]
	s_nop 10
	v_fmac_f32_e32 v125, 0x3e38aa3b, v48
	v_cndmask_b32_e32 v48, v228, v125, vcc
	v_cmp_gt_i32_e32 vcc, s2, v117
	v_fmac_f32_e32 v126, 0x3e38aa3b, v49
	v_fmac_f32_e32 v127, 0x3e38aa3b, v32
	v_cndmask_b32_e32 v125, v228, v127, vcc
	v_fmamk_f32 v127, v129, 0x42040000, v130
	v_cmp_gt_i32_e32 vcc, 0, v117
	v_fmac_f32_e32 v127, 0x3e38aa3b, v33
	v_max_f32_e32 v32, v48, v125
	v_cndmask_b32_e32 v49, v228, v126, vcc
	v_cmp_gt_i32_e32 vcc, s75, v117
	v_fmac_f32_e32 v128, 0x3e38aa3b, v35
	v_fmamk_f32 v35, v129, 0x42240000, v130
	v_cndmask_b32_e32 v126, v228, v127, vcc
	v_max_f32_e32 v33, v49, v126
	v_max3_f32 v32, v32, s1, v33
	v_fma_f32 v33, 2.0, v129, v130
	v_fmac_f32_e32 v33, 0x3e38aa3b, v50
	v_fmamk_f32 v127, v129, 0x42080000, v130
	v_cmp_gt_i32_e32 vcc, -1, v117
	v_fmac_f32_e32 v127, 0x3e38aa3b, v34
	v_fmamk_f32 v34, v129, 0x40400000, v130
	v_cndmask_b32_e32 v50, v228, v33, vcc
	v_cmp_gt_i32_e32 vcc, s72, v117
	v_fmac_f32_e32 v34, 0x3e38aa3b, v51
	v_fmac_f32_e32 v35, 0x3e38aa3b, v37
	v_cndmask_b32_e32 v127, v228, v127, vcc
	v_cmp_gt_i32_e32 vcc, -2, v117
	v_max_f32_e32 v33, v50, v127
	s_nop 0
	v_cndmask_b32_e32 v51, v228, v34, vcc
	v_cmp_gt_i32_e32 vcc, s74, v117
	s_nop 1
	v_cndmask_b32_e32 v128, v228, v128, vcc
	v_max_f32_e32 v34, v51, v128
	v_max3_f32 v32, v32, v33, v34
	v_fmamk_f32 v33, v129, 0x41000000, v130
	v_fmac_f32_e32 v33, 0x3e38aa3b, v52
	v_fmamk_f32 v34, v129, 0x42200000, v130
	v_cmp_gt_i32_e32 vcc, -7, v117
	v_fmac_f32_e32 v34, 0x3e38aa3b, v36
	s_nop 0
	v_cndmask_b32_e32 v36, v228, v33, vcc
	v_cmp_gt_i32_e32 vcc, s3, v117
	s_nop 1
	v_cndmask_b32_e32 v52, v228, v34, vcc
	v_fmamk_f32 v34, v129, 0x41100000, v130
	v_fmac_f32_e32 v34, 0x3e38aa3b, v53
	v_cmp_gt_i32_e32 vcc, -8, v117
	v_max_f32_e32 v33, v36, v52
	s_nop 0
	v_cndmask_b32_e32 v37, v228, v34, vcc
	v_cmp_gt_i32_e32 vcc, s78, v117
	s_nop 1
	v_cndmask_b32_e32 v53, v228, v35, vcc
	v_max_f32_e32 v34, v37, v53
	v_max3_f32 v32, v32, v33, v34
	v_fmamk_f32 v33, v129, 0x41200000, v130
	v_fmac_f32_e32 v33, 0x3e38aa3b, v54
	v_fmamk_f32 v34, v129, 0x42280000, v130
	v_cmp_gt_i32_e32 vcc, -9, v117
	v_fmac_f32_e32 v34, 0x3e38aa3b, v38
	v_fmamk_f32 v35, v129, 0x422c0000, v130
	v_cndmask_b32_e32 v38, v228, v33, vcc
	v_cmp_gt_i32_e32 vcc, s80, v117
	v_fmac_f32_e32 v35, 0x3e38aa3b, v39
	s_nop 0
	v_cndmask_b32_e32 v54, v228, v34, vcc
	v_fmamk_f32 v34, v129, 0x41300000, v130
	v_fmac_f32_e32 v34, 0x3e38aa3b, v55
	v_cmp_gt_i32_e32 vcc, -10, v117
	v_max_f32_e32 v33, v38, v54
	s_nop 0
	v_cndmask_b32_e32 v39, v228, v34, vcc
	v_cmp_gt_i32_e32 vcc, s73, v117
	s_nop 1
	v_cndmask_b32_e32 v55, v228, v35, vcc
	v_max_f32_e32 v34, v39, v55
	v_max3_f32 v32, v32, v33, v34
	v_fmamk_f32 v33, v129, 0x41800000, v130
	v_fmac_f32_e32 v33, 0x3e38aa3b, v56
	v_fmamk_f32 v34, v129, 0x42400000, v130
	v_cmp_gt_i32_e32 vcc, -15, v117
	v_fmac_f32_e32 v34, 0x3e38aa3b, v40
	v_fmamk_f32 v35, v129, 0x42440000, v130
	v_cndmask_b32_e32 v40, v228, v33, vcc
	v_cmp_gt_i32_e32 vcc, s44, v117
	v_fmac_f32_e32 v35, 0x3e38aa3b, v41
	s_nop 0
	v_cndmask_b32_e32 v56, v228, v34, vcc
	v_fmamk_f32 v34, v129, 0x41880000, v130
	v_fmac_f32_e32 v34, 0x3e38aa3b, v57
	v_cmp_gt_i32_e32 vcc, -16, v117
	v_max_f32_e32 v33, v40, v56
	s_nop 0
	v_cndmask_b32_e32 v41, v228, v34, vcc
	v_cmp_gt_i32_e32 vcc, s76, v117
	s_nop 1
	v_cndmask_b32_e32 v57, v228, v35, vcc
	v_max_f32_e32 v34, v41, v57
	v_max3_f32 v32, v32, v33, v34
	v_fmamk_f32 v33, v129, 0x41900000, v130
	v_fmac_f32_e32 v33, 0x3e38aa3b, v58
	v_fmamk_f32 v34, v129, 0x42480000, v130
	v_cmp_gt_i32_e32 vcc, s88, v117
	v_fmac_f32_e32 v34, 0x3e38aa3b, v42
	v_fmamk_f32 v35, v129, 0x424c0000, v130
	v_cndmask_b32_e32 v42, v228, v33, vcc
; template <int MASK>
; __device__ __forceinline__ void tile_qk(const KFr& f, const bf16x8 (&qf)[4], u32x4 (&pw)[4], f32x16& o0, f32x16& o1, float& m, float& l, int kq, float sl2, int lane) {
;     ...
; #pragma unroll
;     for (int r = 0; r < 16; ++r) {
;         const int kk = (r & 3) + 8 * (r >> 2);
;         float t0 = fmaf(p0[r], C2, fmaf((float)kk, sl, base)), t1 = fmaf(p1[r], C2, fmaf((float)(kk + 32), sl, base));
;         if (MASK == 1) { if (dk0 + kk > 0) t0 = NEG; if (dk0 + kk + 32 > 0) t1 = NEG; }
;         p0[r] = t0; p1[r] = t1; mx = fmaxf(mx, fmaxf(t0, t1));
;     }
;     mx = fmaxf(mx, __shfl_xor(mx, 32));
	v_cmp_gt_i32_e32 vcc, s77, v117
	v_fmac_f32_e32 v35, 0x3e38aa3b, v43
	s_nop 0
	v_cndmask_b32_e32 v58, v228, v34, vcc
	v_fmamk_f32 v34, v129, 0x41980000, v130
	v_fmac_f32_e32 v34, 0x3e38aa3b, v59
	v_cmp_gt_i32_e32 vcc, s90, v117
	v_max_f32_e32 v33, v42, v58
	s_nop 0
	v_cndmask_b32_e32 v43, v228, v34, vcc
	v_cmp_gt_i32_e32 vcc, s79, v117
	s_nop 1
	v_cndmask_b32_e32 v59, v228, v35, vcc
	v_max_f32_e32 v34, v43, v59
	v_max3_f32 v32, v32, v33, v34
	v_fmamk_f32 v33, v129, 0x41c00000, v130
	v_fmac_f32_e32 v33, 0x3e38aa3b, v60
	v_fmamk_f32 v34, v129, 0x42600000, v130
	v_cmp_gt_i32_e32 vcc, s45, v117
	v_fmac_f32_e32 v34, 0x3e38aa3b, v44
	v_fmamk_f32 v35, v129, 0x42640000, v130
	v_cndmask_b32_e32 v44, v228, v33, vcc
	v_cmp_gt_i32_e32 vcc, s52, v117
	v_fmac_f32_e32 v35, 0x3e38aa3b, v45
	s_nop 0
	v_cndmask_b32_e32 v60, v228, v34, vcc
	v_fmamk_f32 v34, v129, 0x41c80000, v130
	v_fmac_f32_e32 v34, 0x3e38aa3b, v61
	v_cmp_gt_i32_e32 vcc, s94, v117
	v_max_f32_e32 v33, v44, v60
	s_nop 0
	v_cndmask_b32_e32 v45, v228, v34, vcc
	v_cmp_gt_i32_e32 vcc, s81, v117
	s_nop 1
	v_cndmask_b32_e32 v61, v228, v35, vcc
	v_max_f32_e32 v34, v45, v61
	v_max3_f32 v32, v32, v33, v34
	v_fmamk_f32 v33, v129, 0x41d00000, v130
	v_fmac_f32_e32 v33, 0x3e38aa3b, v62
	v_fmamk_f32 v34, v129, 0x42680000, v130
	v_cmp_gt_i32_e32 vcc, s96, v117
	v_fmac_f32_e32 v34, 0x3e38aa3b, v46
	s_nop 0
	v_cndmask_b32_e32 v46, v228, v33, vcc
	v_cmp_gt_i32_e32 vcc, s82, v117
	s_nop 1
	v_cndmask_b32_e32 v62, v228, v34, vcc
	v_fmamk_f32 v34, v129, 0x41d80000, v130
	v_fmac_f32_e32 v34, 0x3e38aa3b, v63
	v_fmac_f32_e32 v130, 0x426c0000, v129
	v_cmp_gt_i32_e32 vcc, s83, v117
	v_fmac_f32_e32 v130, 0x3e38aa3b, v47
	v_max_f32_e32 v33, v46, v62
	v_cndmask_b32_e32 v47, v228, v34, vcc
	v_cmp_gt_i32_e32 vcc, s84, v117
	v_add_u32_e32 v117, 64, v117
	s_nop 0
	v_cndmask_b32_e32 v63, v228, v130, vcc
	v_max_f32_e32 v34, v47, v63
	v_max3_f32 v32, v32, v33, v34
	v_mbcnt_hi_u32_b32 v34, -1, v220
	v_and_b32_e32 v35, 64, v34
	v_xor_b32_e32 v33, 32, v34
	v_add_u32_e32 v35, 64, v35
	v_cmp_lt_i32_e32 vcc, v33, v35
	s_nop 1
	v_cndmask_b32_e32 v129, v34, v33, vcc
	v_lshlrev_b32_e32 v129, 2, v129
	ds_bpermute_b32 v129, v129, v32
	s_waitcnt lgkmcnt(0)
; __device__ __forceinline__ unsigned pk2(float lo, float hi) { return pg8::cvt_pk_bf16(lo, hi); }
; template <int MASK>
; __device__ __forceinline__ void tile_qk(const KFr& f, const bf16x8 (&qf)[4], u32x4 (&pw)[4], f32x16& o0, f32x16& o1, float& m, float& l, int kq, float sl2, int lane) {
;     ...
;     mx = fmaxf(mx, __shfl_xor(mx, 32));
;     const float mn = fmaxf(m, mx), alpha = __builtin_amdgcn_exp2f(m - mn); m = mn;
;     float rs = 0.f;
; #pragma unroll
;     for (int r = 0; r < 16; ++r) { p0[r] = __builtin_amdgcn_exp2f(p0[r] - mn); p1[r] = __builtin_amdgcn_exp2f(p1[r] - mn); rs += p0[r] + p1[r]; }
;     l = l * alpha + rs;
; #pragma unroll
;     for (int r = 0; r < 16; ++r) { o0[r] *= alpha; o1[r] *= alpha; }
;     pw[0] = (u32x4){pk2(p0[0], p0[1]), pk2(p0[2], p0[3]), pk2(p0[4], p0[5]), pk2(p0[6], p0[7])};
;     pw[1] = (u32x4){pk2(p0[8], p0[9]), pk2(p0[10], p0[11]), pk2(p0[12], p0[13]), pk2(p0[14], p0[15])};
;     pw[2] = (u32x4){pk2(p1[0], p1[1]), pk2(p1[2], p1[3]), pk2(p1[4], p1[5]), pk2(p1[6], p1[7])};
;     pw[3] = (u32x4){pk2(p1[8], p1[9]), pk2(p1[10], p1[11]), pk2(p1[12], p1[13]), pk2(p1[14], p1[15])};
; __device__ __forceinline__ void tile_pv(const VFr& f, const u32x4 (&pw)[4], f32x16& o0, f32x16& o1) {
; #pragma unroll
;     for (int ks = 0; ks < 4; ++ks) {
;         const bf16x8 P = __builtin_bit_cast(bf16x8, pw[ks]);
;         o0 = __builtin_amdgcn_mfma_f32_32x32x16_bf16(f.a[0][ks], P, o0, 0, 0, 0);
;         o1 = __builtin_amdgcn_mfma_f32_32x32x16_bf16(f.a[1][ks], P, o1, 0, 0, 0);
;     }
	v_max3_f32 v32, v124, v32, v129
	v_sub_f32_e32 v48, v48, v32
	v_exp_f32_e32 v130, v48
	v_sub_f32_e32 v48, v125, v32
	v_sub_f32_e32 v49, v49, v32
	v_exp_f32_e32 v131, v48
	v_exp_f32_e32 v132, v49
	v_sub_f32_e32 v49, v126, v32
	v_exp_f32_e32 v133, v49
	v_add_f32_e32 v48, v131, v130
	v_add_f32_e32 v48, 0, v48
	v_sub_f32_e32 v36, v36, v32
	v_add_f32_e32 v49, v133, v132
	v_add_f32_e32 v48, v49, v48
	v_sub_f32_e32 v49, v50, v32
	v_exp_f32_e32 v134, v49
	v_sub_f32_e32 v49, v127, v32
	v_exp_f32_e32 v135, v49
	v_sub_f32_e32 v129, v124, v32
	v_add_f32_e32 v49, v135, v134
	v_add_f32_e32 v48, v49, v48
	v_sub_f32_e32 v49, v51, v32
	v_exp_f32_e32 v51, v49
	v_sub_f32_e32 v49, v128, v32
	v_exp_f32_e32 v128, v49
	s_nop 0
	v_add_f32_e32 v49, v128, v51
	v_add_f32_e32 v50, v49, v48
	v_exp_f32_e32 v49, v36
	v_sub_f32_e32 v36, v52, v32
	v_exp_f32_e32 v125, v36
	v_sub_f32_e32 v36, v37, v32
	v_exp_f32_e32 v48, v36
	v_sub_f32_e32 v36, v53, v32
	v_exp_f32_e32 v124, v36
	s_nop 0
	v_pk_add_f32 v[36:37], v[124:125], v[48:49]
	s_nop 0
	v_add_f32_e32 v37, v37, v50
	v_add_f32_e32 v50, v36, v37
	v_sub_f32_e32 v36, v38, v32
	v_exp_f32_e32 v37, v36
	v_sub_f32_e32 v36, v54, v32
	v_exp_f32_e32 v53, v36
	v_sub_f32_e32 v36, v39, v32
	v_sub_f32_e32 v38, v55, v32
	v_exp_f32_e32 v36, v36
	v_exp_f32_e32 v52, v38
	s_nop 0
	v_pk_add_f32 v[38:39], v[52:53], v[36:37]
	s_nop 0
	v_add_f32_e32 v39, v39, v50
	v_add_f32_e32 v50, v38, v39
	v_sub_f32_e32 v38, v40, v32
	v_exp_f32_e32 v39, v38
	v_sub_f32_e32 v38, v56, v32
	v_exp_f32_e32 v55, v38
	v_sub_f32_e32 v38, v41, v32
	v_sub_f32_e32 v40, v57, v32
	v_exp_f32_e32 v38, v38
	v_exp_f32_e32 v54, v40
	v_pk_mov_b32 v[52:53], v[52:53], v[52:53] op_sel:[1,0]
	v_pk_add_f32 v[40:41], v[54:55], v[38:39]
	s_nop 0
	v_add_f32_e32 v41, v41, v50
	v_add_f32_e32 v50, v40, v41
	v_sub_f32_e32 v40, v42, v32
	v_exp_f32_e32 v41, v40
	v_sub_f32_e32 v40, v58, v32
	v_exp_f32_e32 v57, v40
	v_sub_f32_e32 v40, v43, v32
	v_sub_f32_e32 v42, v59, v32
	v_exp_f32_e32 v40, v40
	v_exp_f32_e32 v56, v42
	v_pk_mov_b32 v[54:55], v[54:55], v[54:55] op_sel:[1,0]
	v_pk_mov_b32 v[126:127], v[40:41], v[40:41] op_sel:[1,0]
	v_pk_add_f32 v[42:43], v[56:57], v[40:41]
	v_cvt_pk_bf16_f32 v41, v126, v127
	v_add_f32_e32 v43, v43, v50
	v_add_f32_e32 v50, v42, v43
	v_sub_f32_e32 v42, v44, v32
	v_exp_f32_e32 v43, v42
	v_sub_f32_e32 v42, v60, v32
	v_exp_f32_e32 v59, v42
	v_sub_f32_e32 v42, v45, v32
	v_sub_f32_e32 v44, v61, v32
	v_exp_f32_e32 v42, v42
	v_exp_f32_e32 v58, v44
	v_pk_mov_b32 v[56:57], v[56:57], v[56:57] op_sel:[1,0]
	v_pk_add_f32 v[44:45], v[58:59], v[42:43]
	s_nop 0
	v_add_f32_e32 v45, v45, v50
	v_add_f32_e32 v50, v44, v45
	v_sub_f32_e32 v44, v46, v32
	v_exp_f32_e32 v45, v44
	v_sub_f32_e32 v44, v62, v32
	v_exp_f32_e32 v61, v44
	v_sub_f32_e32 v44, v47, v32
	v_sub_f32_e32 v46, v63, v32
	v_exp_f32_e32 v44, v44
	v_exp_f32_e32 v60, v46
	v_pk_mov_b32 v[62:63], v[36:37], v[36:37] op_sel:[1,0]
	v_cvt_pk_bf16_f32 v36, v130, v132
	v_cvt_pk_bf16_f32 v37, v134, v51
	v_pk_add_f32 v[46:47], v[60:61], v[44:45]
	v_pk_mov_b32 v[42:43], v[42:43], v[42:43] op_sel:[1,0]
	v_add_f32_e32 v47, v47, v50
	v_add_f32_e32 v50, v46, v47
	v_exp_f32_e32 v46, v129
	v_pk_mov_b32 v[44:45], v[44:45], v[44:45] op_sel:[1,0]
	v_cvt_pk_bf16_f32 v42, v42, v43
	v_cvt_pk_bf16_f32 v43, v44, v45
	v_fmac_f32_e32 v50, v123, v46
	v_pk_mul_f32 v[30:31], v[30:31], v[46:47] op_sel_hi:[1,0]
	v_pk_mul_f32 v[28:29], v[28:29], v[46:47] op_sel_hi:[1,0]
	v_pk_mul_f32 v[26:27], v[26:27], v[46:47] op_sel_hi:[1,0]
	v_pk_mul_f32 v[24:25], v[24:25], v[46:47] op_sel_hi:[1,0]
	v_pk_mul_f32 v[22:23], v[22:23], v[46:47] op_sel_hi:[1,0]
	v_pk_mul_f32 v[20:21], v[20:21], v[46:47] op_sel_hi:[1,0]
	v_pk_mul_f32 v[18:19], v[18:19], v[46:47] op_sel_hi:[1,0]
	v_pk_mul_f32 v[16:17], v[16:17], v[46:47] op_sel_hi:[1,0]
	v_pk_mul_f32 v[14:15], v[14:15], v[46:47] op_sel_hi:[1,0]
	v_pk_mul_f32 v[12:13], v[12:13], v[46:47] op_sel_hi:[1,0]
	v_pk_mul_f32 v[10:11], v[10:11], v[46:47] op_sel_hi:[1,0]
	v_pk_mul_f32 v[8:9], v[8:9], v[46:47] op_sel_hi:[1,0]
	v_pk_mul_f32 v[6:7], v[6:7], v[46:47] op_sel_hi:[1,0]
	v_pk_mul_f32 v[4:5], v[4:5], v[46:47] op_sel_hi:[1,0]
	v_pk_mul_f32 v[2:3], v[2:3], v[46:47] op_sel_hi:[1,0]
	v_pk_mul_f32 v[0:1], v[0:1], v[46:47] op_sel_hi:[1,0]
	v_pk_mov_b32 v[46:47], v[48:49], v[48:49] op_sel:[1,0]
	v_pk_mov_b32 v[48:49], v[124:125], v[124:125] op_sel:[1,0]
	v_pk_mov_b32 v[124:125], v[38:39], v[38:39] op_sel:[1,0]
	v_cvt_pk_bf16_f32 v38, v46, v47
	v_cvt_pk_bf16_f32 v39, v62, v63
	v_cvt_pk_bf16_f32 v40, v124, v125
	v_cvt_pk_bf16_f32 v44, v131, v133
	v_mfma_f32_32x32x16_bf16 v[16:31], v[94:97], v[36:39], v[16:31]
	v_cvt_pk_bf16_f32 v45, v135, v128
	v_cvt_pk_bf16_f32 v46, v48, v49
	v_cvt_pk_bf16_f32 v47, v52, v53
	v_pk_mov_b32 v[58:59], v[58:59], v[58:59] op_sel:[1,0]
	v_pk_mov_b32 v[60:61], v[60:61], v[60:61] op_sel:[1,0]
	v_cvt_pk_bf16_f32 v52, v54, v55
	v_cvt_pk_bf16_f32 v53, v56, v57
	v_mfma_f32_32x32x16_bf16 v[0:15], v[110:113], v[36:39], v[0:15]
	v_cvt_pk_bf16_f32 v54, v58, v59
	v_cvt_pk_bf16_f32 v55, v60, v61
	v_mfma_f32_32x32x16_bf16 v[16:31], v[90:93], v[40:43], v[16:31]
	v_mfma_f32_32x32x16_bf16 v[0:15], v[106:109], v[40:43], v[0:15]
	v_mfma_f32_32x32x16_bf16 v[16:31], v[86:89], v[44:47], v[16:31]
	v_mfma_f32_32x32x16_bf16 v[0:15], v[102:105], v[44:47], v[0:15]
	v_mfma_f32_32x32x16_bf16 v[16:31], v[82:85], v[52:55], v[16:31]
	v_mfma_f32_32x32x16_bf16 v[0:15], v[98:101], v[52:55], v[0:15]
	s_cbranch_scc0 .LBB0_268
	s_mov_b64 s[0:1], 0

; __device__ __forceinline__ unsigned pk2(float lo, float hi) { return pg8::cvt_pk_bf16(lo, hi); }
; #define TASK_ADV() do { have = false; for (;;) { ++ch; ++k; while (n < qb && ch >= ((c + 31) >> 5)) { ++n; ch = 0; c = (n < qb) ? (int)CNT[n] : 0; } \
;                         if (n >= qb) break; if ((k & 7) == wave) { have = true; break; } } } while (0)
; #define TASK_Q(Q2, VALID, QG) do { const int idx_ = ch * 32 + r32; VALID = idx_ < c; Q2 = (int)LIST[n * 256 + (VALID ? idx_ : ch * 32)]; \
;                         const bf16* qp_ = qkv + ((size_t)b * SEQ + 256 * qb + Q2) * PA + C_CQ + h * 64 + hi * 8; \
;                         _Pragma("unroll") for (int d0 = 0; d0 < 4; ++d0) QG[d0] = *(const bf16x8*)(qp_ + 16 * d0); } while (0)
; __device__ __forceinline__ void moba_unit(int b, int h, int qb, const bf16* qkv, const bf16* KF, const bf16* VF, bf16* Y, const float* kmean, LAS unsigned char* lds) {
;     ...
;         { const float xs = sl2 * (1.f / (0.125f * LOG2E)); const unsigned shb = pk2(xs, 0.f) & 0xffffu; const float res = xs - __uint_as_float(shb << 16);
;           const unsigned qw = (hi == 0) ? (shb | (pk2(res, 0.f) << 16)) : 0u;
;           const unsigned k0w = (hi == 0) ? pk2((float)r32, (float)r32) : 0u, k1w = (hi == 0) ? pk2((float)(r32 + 32), (float)(r32 + 32)) : 0u;
;           qx = __builtin_bit_cast(bf16x8, (u32x4){qw, 0u, 0u, 0u}); kx0 = __builtin_bit_cast(bf16x8, (u32x4){k0w, 0u, 0u, 0u}); kx1 = __builtin_bit_cast(bf16x8, (u32x4){k1w, 0u, 0u, 0u}); }
;         int n = 0, ch = -1, k = -1, c = (qb > 0) ? (int)CNT[0] : 0; bool have = false;
;     ...
;         TASK_ADV();
;         bf16x8 qg[4]; int q2 = 0; bool valid = false; KFr k0, k1; VFr v0; u32x4 pw[4];
;         const char* kp = (const char*)KFh + lane * 16; const char* vp = (const char*)VFh + lane * 16;
;         if (have) { TASK_Q(q2, valid, qg); kp += (size_t)(4 * n) * 8192; asm volatile("" : "+v"(kp)); loadK(k0, kp); }
.LBB0_327:
	s_andn2_b64 vcc, exec, s[2:3]
	s_cbranch_vccz .LBB0_361
	v_and_b32_e32 v232, 31, v0
	s_lshl_b32 s2, s26, 5
	s_waitcnt lgkmcnt(0)
	v_or_b32_e32 v2, s2, v232
	s_lshl_b32 s12, s25, 8
	v_mov_b32_e32 v3, s2
	v_cmp_lt_i32_e64 s[2:3], v2, v231
	s_add_i32 s12, s12, 0
	v_lshlrev_b32_e32 v64, 4, v1
	v_cndmask_b32_e64 v2, v3, v2, s[2:3]
	v_add_u32_e32 v2, s12, v2
	v_add_u32_e32 v2, 0x1b000, v2
	ds_read_u8 v216, v2
	v_mov_b64_e32 v[2:3], s[36:37]
	s_movk_i32 s12, 0x1e00
	v_lshrrev_b32_e32 v0, 2, v0
	s_lshl_b32 s46, s20, 1
	s_waitcnt lgkmcnt(0)
	v_or_b32_e32 v1, s22, v216
	v_or_b32_e32 v1, s6, v1
	v_mad_u64_u32 v[2:3], s[12:13], v1, s12, v[2:3]
	v_mad_i32_i24 v3, s7, v226, v3
	v_and_b32_e32 v0, 8, v0
	v_lshl_add_u64 v[2:3], v[2:3], 0, s[46:47]
	s_waitcnt vmcnt(0)
	v_lshlrev_b32_e32 v4, 1, v0
	v_mov_b32_e32 v5, v65
	v_lshl_add_u64 v[2:3], v[2:3], 0, v[4:5]
	s_mov_b64 s[12:13], 0x1200
	v_lshl_add_u64 v[4:5], v[2:3], 0, s[12:13]
	s_movk_i32 s12, 0x1000
	v_add_co_u32_e32 v2, vcc, s12, v2
	s_lshl_b32 s12, s25, 2
	s_ashr_i32 s13, s12, 31
	v_lshl_add_u64 v[208:209], s[10:11], 0, v[64:65]
	v_addc_co_u32_e32 v3, vcc, 0, v3, vcc
	s_lshl_b64 s[12:13], s[12:13], 13
	global_load_dwordx4 v[78:81], v[4:5], off offset:32
	global_load_dwordx4 v[82:85], v[4:5], off offset:64
	global_load_dwordx4 v[86:89], v[2:3], off offset:512
	global_load_dwordx4 v[90:93], v[4:5], off offset:96
	v_lshl_add_u64 v[2:3], v[208:209], 0, s[12:13]
	global_load_dwordx4 v[106:109], v[2:3], off
	global_load_dwordx4 v[102:105], v[2:3], off offset:1024
	global_load_dwordx4 v[98:101], v[2:3], off offset:2048
	global_load_dwordx4 v[94:97], v[2:3], off offset:3072
	v_lshl_add_u64 v[2:3], v[2:3], 0, s[56:57]
	global_load_dwordx4 v[122:125], v[2:3], off
	global_load_dwordx4 v[118:121], v[2:3], off offset:1024
	global_load_dwordx4 v[114:117], v[2:3], off offset:2048
	global_load_dwordx4 v[110:113], v[2:3], off offset:3072
	v_cvt_f32_ubyte0_e32 v1, v232
	v_cvt_pk_bf16_f32 v1, v1, v1
	v_cndmask_b32_e64 v70, 0, v1, s[0:1]
	v_or_b32_e32 v1, 32, v232
	v_cvt_f32_ubyte0_e32 v1, v1
	v_cvt_pk_bf16_f32 v1, v1, v1
	v_cndmask_b32_e64 v74, 0, v1, s[0:1]
	v_mov_b32_e32 v67, v65
	v_mov_b32_e32 v68, v65
	v_mov_b32_e32 v69, v65
	v_mov_b32_e32 v71, v65
	v_mov_b32_e32 v72, v65
	v_mov_b32_e32 v73, v65
	v_mov_b32_e32 v75, v65
	v_mov_b32_e32 v76, v65
	v_mov_b32_e32 v77, v65
	v_lshl_add_u64 v[214:215], v[2:3], 0, s[56:57]
	v_lshl_add_u64 v[210:211], s[8:9], 0, v[64:65]
	v_add_u32_e32 v233, 0, v0
	v_lshlrev_b32_e32 v212, 1, v0
	s_branch .LBB0_330

; #define SB_() __builtin_amdgcn_sched_barrier(0)
; __device__ __forceinline__ void tile_qk_fast(const KFr& f, const bf16x8 (&qf)[4], const bf16x8& kx0, const bf16x8& kx1, const bf16x8& qx, u32x4 (&pw)[4],
;                                              f32x16& o0, f32x16& o1, float& m, float& l, float off) {
;     ...
;     p0 = __builtin_amdgcn_mfma_f32_32x32x16_bf16(kx0, qx, p0, 0, 0, 0);
;     p1 = __builtin_amdgcn_mfma_f32_32x32x16_bf16(kx1, qx, p1, 0, 0, 0);
; #pragma unroll
;     for (int d0 = 0; d0 < 4; ++d0) {
;         p0 = __builtin_amdgcn_mfma_f32_32x32x16_bf16(f.a[0][d0], qf[d0], p0, 0, 0, 0);
;         p1 = __builtin_amdgcn_mfma_f32_32x32x16_bf16(f.a[1][d0], qf[d0], p1, 0, 0, 0);
;     }
;     constexpr float C2 = 0.125f * LOG2E;
;     float mr = fmaxf(p0[0], p1[0]);
; #pragma unroll
;     for (int r = 1; r < 16; ++r) mr = fmaxf(fmaxf(mr, p0[r]), p1[r]);
;     float mx = fmaf(mr, C2, off);
;     mx = fmaxf(mx, __shfl_xor(mx, 32));
;     const float mn = fmaxf(m, mx);
;     if (__ballot(mn > m) != 0ull) {
;         const float alpha = __builtin_amdgcn_exp2f(m - mn); l *= alpha;
; #pragma unroll
;         for (int r = 0; r < 16; ++r) { o0[r] *= alpha; o1[r] *= alpha; }
;     }
;     m = mn;
;     const float sh = off - mn;
;     float rs = 0.f;
; #pragma unroll
;     for (int r = 0; r < 16; ++r) { p0[r] = __builtin_amdgcn_exp2f(fmaf(p0[r], C2, sh)); p1[r] = __builtin_amdgcn_exp2f(fmaf(p1[r], C2, sh)); rs += p0[r] + p1[r]; }
; __device__ __forceinline__ void moba_unit(int b, int h, int qb, const bf16* qkv, const bf16* KF, const bf16* VF, bf16* Y, const float* kmean, LAS unsigned char* lds) {
;     ...
;             const int n_c = n; const bool valid_c = valid; const int q2_c = q2;
;             vp = (const char*)VFh + (size_t)(4 * n_c) * 8192 + lane * 16; asm volatile("" : "+v"(vp));
;             float m2 = -1e30f, l2 = 0.f; f32x16 a0, a1;
; #pragma unroll
;             for (int r = 0; r < 16; ++r) { a0[r] = 0.f; a1[r] = 0.f; }
;             const int kq0 = 256 * n_c - (256 * qb + q2_c);
;             TASK_ADV();
;             loadV(v0, vp); SB_();
;             loadK(k1, kp); SB_(); tile_qk_fast(k0, qg, kx0, kx1, qx, pw, a0, a1, m2, l2, sl2 * (float)(kq0)); SB_();
.LBB0_349:
	global_load_dwordx4 v[162:165], v[0:1], off
	global_load_dwordx4 v[154:157], v[0:1], off offset:1024
	global_load_dwordx4 v[146:149], v[0:1], off offset:2048
	global_load_dwordx4 v[142:145], v[0:1], off offset:3072
	v_lshl_add_u64 v[0:1], v[0:1], 0, s[56:57]
	global_load_dwordx4 v[170:173], v[0:1], off
	global_load_dwordx4 v[166:169], v[0:1], off offset:1024
	global_load_dwordx4 v[158:161], v[0:1], off offset:2048
	global_load_dwordx4 v[150:153], v[0:1], off offset:3072
	s_sub_i32 s2, s27, s21
	s_lshl_b32 s2, s2, 8
	v_sub_u32_e32 v236, s2, v234
	v_lshl_add_u64 v[216:217], v[0:1], 0, s[56:57]
	v_lshl_add_u64 v[0:1], v[214:215], 0, s[56:57]
	global_load_dwordx4 v[194:197], v[214:215], off
	global_load_dwordx4 v[186:189], v[214:215], off offset:1024
	global_load_dwordx4 v[182:185], v[214:215], off offset:2048
	global_load_dwordx4 v[174:177], v[214:215], off offset:3072
	global_load_dwordx4 v[202:205], v[0:1], off
	global_load_dwordx4 v[198:201], v[0:1], off offset:1024
	global_load_dwordx4 v[190:193], v[0:1], off offset:2048
	global_load_dwordx4 v[178:181], v[0:1], off offset:3072
	v_lshl_add_u64 v[218:219], v[0:1], 0, s[56:57]
	v_mfma_f32_32x32x16_bf16 v[48:63], v[70:73], v[66:69], 0
	v_cvt_f32_i32_e32 v64, v236
	s_mov_b32 s2, 0xf149f2ca
	s_waitcnt lgkmcnt(0)
	v_mfma_f32_32x32x16_bf16 v[32:47], v[74:77], v[66:69], 0
	s_waitcnt lgkmcnt(0)
	v_mfma_f32_32x32x16_bf16 v[16:31], v[106:109], v[138:141], v[48:63]
	v_mfma_f32_32x32x16_bf16 v[0:15], v[122:125], v[138:141], v[32:47]
	v_mfma_f32_32x32x16_bf16 v[16:31], v[102:105], v[134:137], v[16:31]
	v_mfma_f32_32x32x16_bf16 v[0:15], v[118:121], v[134:137], v[0:15]
	v_mfma_f32_32x32x16_bf16 v[16:31], v[98:101], v[130:133], v[16:31]
	v_mul_f32_e32 v98, v230, v64
	v_mfma_f32_32x32x16_bf16 v[0:15], v[114:117], v[130:133], v[0:15]
	v_mfma_f32_32x32x16_bf16 v[0:15], v[110:113], v[126:129], v[0:15]
	v_mfma_f32_32x32x16_bf16 v[16:31], v[94:97], v[126:129], v[16:31]
	s_nop 10
	v_max_f32_e32 v99, v0, v0
	v_max_f32_e32 v94, v16, v16
	v_max_f32_e32 v94, v94, v99
	v_max3_f32 v94, v94, v17, v1
	v_max3_f32 v94, v94, v18, v2
	v_max3_f32 v94, v94, v19, v3
	v_max3_f32 v94, v94, v20, v4
	v_max3_f32 v94, v94, v21, v5
	v_max3_f32 v94, v94, v22, v6
	v_max3_f32 v94, v94, v23, v7
	v_max3_f32 v94, v94, v24, v8
	v_max3_f32 v94, v94, v25, v9
	v_max3_f32 v94, v94, v26, v10
	v_max3_f32 v94, v94, v27, v11
	v_max3_f32 v94, v94, v28, v12
	v_max3_f32 v94, v94, v29, v13
	v_max3_f32 v94, v94, v30, v14
	v_max3_f32 v94, v94, v31, v15
	v_fmac_f32_e32 v98, 0x3e38aa3b, v94
	v_mbcnt_hi_u32_b32 v94, -1, v220
	v_and_b32_e32 v96, 64, v94
	v_xor_b32_e32 v95, 32, v94
	v_add_u32_e32 v96, 64, v96
	v_cmp_lt_i32_e32 vcc, v95, v96
	s_nop 1
	v_cndmask_b32_e32 v94, v94, v95, vcc
	v_lshlrev_b32_e32 v235, 2, v94
	ds_bpermute_b32 v94, v235, v98
	s_waitcnt lgkmcnt(0)
	v_max3_f32 v238, v98, v94, s2
	v_fma_f32 v110, v230, v64, -v238
	v_fmamk_f32 v0, v0, 0x3e38aa3b, v110
	v_sub_f32_e32 v94, 0xf149f2ca, v238
	v_fmamk_f32 v16, v16, 0x3e38aa3b, v110
	v_exp_f32_e32 v112, v0
	v_fmamk_f32 v0, v17, 0x3e38aa3b, v110
	v_exp_f32_e32 v94, v94
	v_exp_f32_e32 v111, v16
	v_exp_f32_e32 v64, v0
	v_fmamk_f32 v0, v1, 0x3e38aa3b, v110
	v_exp_f32_e32 v16, v0
	v_cmp_lt_f32_e32 vcc, s2, v238
	s_cmp_lg_u64 vcc, 0
	v_mul_f32_e32 v94, 0, v94
	s_cselect_b64 vcc, -1, 0
	v_add_f32_e32 v17, v112, v111
	v_cndmask_b32_e32 v0, 0, v94, vcc
	v_pk_add_f32 v[94:95], v[16:17], v[64:65]
	v_fmamk_f32 v2, v2, 0x3e38aa3b, v110
	v_pk_add_f32 v[96:97], v[94:95], v[94:95] op_sel_hi:[0,1]
	v_fmamk_f32 v17, v18, 0x3e38aa3b, v110
	v_exp_f32_e32 v113, v2
	v_fmamk_f32 v2, v19, 0x3e38aa3b, v110
	v_exp_f32_e32 v17, v17
	v_exp_f32_e32 v96, v2
	v_fmamk_f32 v2, v3, 0x3e38aa3b, v110
	v_exp_f32_e32 v18, v2
	v_add_f32_e32 v19, v113, v17
	v_fmamk_f32 v4, v4, 0x3e38aa3b, v110
	v_exp_f32_e32 v114, v4
	v_pk_add_f32 v[94:95], v[18:19], v[96:97]
	v_fmamk_f32 v19, v20, 0x3e38aa3b, v110
	v_pk_add_f32 v[98:99], v[94:95], v[94:95] op_sel_hi:[0,1]
	v_exp_f32_e32 v19, v19
	v_fmamk_f32 v4, v21, 0x3e38aa3b, v110
	v_fmamk_f32 v5, v5, 0x3e38aa3b, v110
	v_exp_f32_e32 v98, v4
	v_exp_f32_e32 v20, v5
	v_add_f32_e32 v21, v114, v19
	v_fmamk_f32 v6, v6, 0x3e38aa3b, v110
	v_exp_f32_e32 v115, v6
	v_pk_add_f32 v[94:95], v[20:21], v[98:99]
	v_fmamk_f32 v21, v22, 0x3e38aa3b, v110
	v_pk_add_f32 v[100:101], v[94:95], v[94:95] op_sel_hi:[0,1]
	v_fmamk_f32 v6, v23, 0x3e38aa3b, v110
	v_exp_f32_e32 v21, v21
	v_exp_f32_e32 v100, v6
	v_fmamk_f32 v6, v7, 0x3e38aa3b, v110
	v_exp_f32_e32 v22, v6
	v_add_f32_e32 v23, v115, v21
	v_fmamk_f32 v8, v8, 0x3e38aa3b, v110
	v_exp_f32_e32 v116, v8
	v_pk_add_f32 v[94:95], v[22:23], v[100:101]
	v_fmamk_f32 v23, v24, 0x3e38aa3b, v110
	v_pk_add_f32 v[102:103], v[94:95], v[94:95] op_sel_hi:[0,1]
	v_fmamk_f32 v8, v25, 0x3e38aa3b, v110
	v_exp_f32_e32 v23, v23
	v_exp_f32_e32 v102, v8
	v_fmamk_f32 v8, v9, 0x3e38aa3b, v110
	v_exp_f32_e32 v24, v8
	v_add_f32_e32 v25, v116, v23
	v_fmamk_f32 v10, v10, 0x3e38aa3b, v110
	v_exp_f32_e32 v117, v10
	v_pk_add_f32 v[94:95], v[24:25], v[102:103]
	v_fmamk_f32 v25, v26, 0x3e38aa3b, v110
	v_pk_add_f32 v[104:105], v[94:95], v[94:95] op_sel_hi:[0,1]
	v_fmamk_f32 v10, v27, 0x3e38aa3b, v110
	v_exp_f32_e32 v25, v25
	v_exp_f32_e32 v104, v10
	v_fmamk_f32 v10, v11, 0x3e38aa3b, v110
	v_exp_f32_e32 v26, v10
	v_add_f32_e32 v27, v117, v25
	v_fmamk_f32 v12, v12, 0x3e38aa3b, v110
	v_exp_f32_e32 v118, v12
	v_pk_add_f32 v[94:95], v[26:27], v[104:105]
	v_fmamk_f32 v27, v28, 0x3e38aa3b, v110
	v_pk_add_f32 v[106:107], v[94:95], v[94:95] op_sel_hi:[0,1]
	v_fmamk_f32 v12, v29, 0x3e38aa3b, v110
	v_exp_f32_e32 v27, v27
	v_exp_f32_e32 v106, v12
	v_fmamk_f32 v12, v13, 0x3e38aa3b, v110
; __device__ __forceinline__ unsigned pk2(float lo, float hi) { return pg8::cvt_pk_bf16(lo, hi); }
; #define SB_() __builtin_amdgcn_sched_barrier(0)
; __device__ __forceinline__ void tile_qk_fast(const KFr& f, const bf16x8 (&qf)[4], const bf16x8& kx0, const bf16x8& kx1, const bf16x8& qx, u32x4 (&pw)[4],
;                                              f32x16& o0, f32x16& o1, float& m, float& l, float off) {
;     ...
;     const float sh = off - mn;
;     float rs = 0.f;
; #pragma unroll
;     for (int r = 0; r < 16; ++r) { p0[r] = __builtin_amdgcn_exp2f(fmaf(p0[r], C2, sh)); p1[r] = __builtin_amdgcn_exp2f(fmaf(p1[r], C2, sh)); rs += p0[r] + p1[r]; }
;     l += rs;
;     pw[0] = (u32x4){pk2(p0[0], p0[1]), pk2(p0[2], p0[3]), pk2(p0[4], p0[5]), pk2(p0[6], p0[7])};
;     pw[1] = (u32x4){pk2(p0[8], p0[9]), pk2(p0[10], p0[11]), pk2(p0[12], p0[13]), pk2(p0[14], p0[15])};
;     pw[2] = (u32x4){pk2(p1[0], p1[1]), pk2(p1[2], p1[3]), pk2(p1[4], p1[5]), pk2(p1[6], p1[7])};
;     pw[3] = (u32x4){pk2(p1[8], p1[9]), pk2(p1[10], p1[11]), pk2(p1[12], p1[13]), pk2(p1[14], p1[15])};
; }
; __device__ __forceinline__ void tile_pv(const VFr& f, const u32x4 (&pw)[4], f32x16& o0, f32x16& o1) {
; #pragma unroll
;     for (int ks = 0; ks < 4; ++ks) {
;         const bf16x8 P = __builtin_bit_cast(bf16x8, pw[ks]);
;         o0 = __builtin_amdgcn_mfma_f32_32x32x16_bf16(f.a[0][ks], P, o0, 0, 0, 0);
;         o1 = __builtin_amdgcn_mfma_f32_32x32x16_bf16(f.a[1][ks], P, o1, 0, 0, 0);
; __device__ __forceinline__ void moba_unit(int b, int h, int qb, const bf16* qkv, const bf16* KF, const bf16* VF, bf16* Y, const float* kmean, LAS unsigned char* lds) {
;     ...
;             tile_pv(v0, pw, a0, a1); SB_();
;             loadV(v0, vp); loadK(k0, kp); SB_(); tile_qk_fast(k1, qg, kx0, kx1, qx, pw, a0, a1, m2, l2, sl2 * (float)(kq0 + 64)); SB_();
	v_exp_f32_e32 v28, v12
	v_add_f32_e32 v29, v118, v27
	v_fmamk_f32 v14, v14, 0x3e38aa3b, v110
	v_exp_f32_e32 v119, v14
	v_pk_add_f32 v[94:95], v[28:29], v[106:107]
	v_fmamk_f32 v29, v30, 0x3e38aa3b, v110
	v_pk_add_f32 v[108:109], v[94:95], v[94:95] op_sel_hi:[0,1]
	v_exp_f32_e32 v29, v29
	v_fmamk_f32 v14, v31, 0x3e38aa3b, v110
	v_fmac_f32_e32 v110, 0x3e38aa3b, v15
	v_exp_f32_e32 v108, v14
	v_exp_f32_e32 v30, v110
	v_add_f32_e32 v31, v119, v29
	v_mov_b32_e32 v1, v0
	v_mov_b32_e32 v2, v0
	v_pk_add_f32 v[94:95], v[30:31], v[108:109]
	v_mov_b32_e32 v3, v0
	v_add_f32_e32 v31, v94, v95
	v_mov_b32_e32 v4, v0
	v_mov_b32_e32 v5, v0
	v_mov_b32_e32 v6, v0
	v_mov_b32_e32 v7, v0
	v_mov_b32_e32 v8, v0
	v_mov_b32_e32 v9, v0
	v_mov_b32_e32 v10, v0
	v_mov_b32_e32 v11, v0
	v_mov_b32_e32 v12, v0
	v_mov_b32_e32 v13, v0
	v_mov_b32_e32 v14, v0
	v_mov_b32_e32 v15, v0
	v_add_f32_e32 v237, v0, v31
	v_cvt_pk_bf16_f32 v94, v111, v64
	v_cvt_pk_bf16_f32 v95, v17, v96
	v_cvt_pk_bf16_f32 v96, v19, v98
	v_cvt_pk_bf16_f32 v97, v21, v100
	v_cvt_pk_bf16_f32 v98, v23, v102
	v_cvt_pk_bf16_f32 v99, v25, v104
	v_cvt_pk_bf16_f32 v100, v27, v106
	v_cvt_pk_bf16_f32 v101, v29, v108
	v_cvt_pk_bf16_f32 v102, v112, v16
	v_cvt_pk_bf16_f32 v103, v113, v18
	v_cvt_pk_bf16_f32 v104, v114, v20
	v_cvt_pk_bf16_f32 v105, v115, v22
	v_cvt_pk_bf16_f32 v106, v116, v24
	v_cvt_pk_bf16_f32 v107, v117, v26
	v_cvt_pk_bf16_f32 v108, v118, v28
	v_cvt_pk_bf16_f32 v109, v119, v30
	s_waitcnt vmcnt(0)
	v_mfma_f32_32x32x16_bf16 v[16:31], v[162:165], v[94:97], v[0:15]
	v_mfma_f32_32x32x16_bf16 v[0:15], v[170:173], v[94:97], v[0:15]
	v_mfma_f32_32x32x16_bf16 v[16:31], v[154:157], v[98:101], v[16:31]
	v_mfma_f32_32x32x16_bf16 v[0:15], v[166:169], v[98:101], v[0:15]
	v_mfma_f32_32x32x16_bf16 v[16:31], v[146:149], v[102:105], v[16:31]
	v_mfma_f32_32x32x16_bf16 v[0:15], v[158:161], v[102:105], v[0:15]
	v_mfma_f32_32x32x16_bf16 v[16:31], v[142:145], v[106:109], v[16:31]
	v_mfma_f32_32x32x16_bf16 v[0:15], v[150:153], v[106:109], v[0:15]
	v_lshl_add_u64 v[94:95], v[216:217], 0, s[56:57]
	global_load_dwordx4 v[162:165], v[216:217], off
	global_load_dwordx4 v[154:157], v[216:217], off offset:1024
	global_load_dwordx4 v[146:149], v[216:217], off offset:2048
	global_load_dwordx4 v[142:145], v[216:217], off offset:3072
	v_lshl_add_u64 v[216:217], v[218:219], 0, s[56:57]
	v_lshl_add_u64 v[214:215], v[94:95], 0, s[56:57]
	global_load_dwordx4 v[170:173], v[94:95], off
	global_load_dwordx4 v[166:169], v[94:95], off offset:1024
	global_load_dwordx4 v[158:161], v[94:95], off offset:2048
	global_load_dwordx4 v[150:153], v[94:95], off offset:3072
	global_load_dwordx4 v[106:109], v[218:219], off
	global_load_dwordx4 v[102:105], v[218:219], off offset:1024
	global_load_dwordx4 v[98:101], v[218:219], off offset:2048
	global_load_dwordx4 v[94:97], v[218:219], off offset:3072
	global_load_dwordx4 v[122:125], v[216:217], off
	global_load_dwordx4 v[118:121], v[216:217], off offset:1024
	global_load_dwordx4 v[114:117], v[216:217], off offset:2048
	global_load_dwordx4 v[110:113], v[216:217], off offset:3072
	v_lshl_add_u64 v[216:217], v[216:217], 0, s[56:57]
	v_mfma_f32_32x32x16_bf16 v[48:63], v[194:197], v[138:141], v[48:63]
	v_add_u32_e32 v64, 64, v236
	v_cvt_f32_i32_e32 v64, v64
	v_mul_f32_e32 v64, v230, v64
	v_mfma_f32_32x32x16_bf16 v[32:47], v[202:205], v[138:141], v[32:47]
	v_mfma_f32_32x32x16_bf16 v[48:63], v[186:189], v[134:137], v[48:63]
	v_mfma_f32_32x32x16_bf16 v[32:47], v[198:201], v[134:137], v[32:47]
	v_mfma_f32_32x32x16_bf16 v[48:63], v[182:185], v[130:133], v[48:63]
	v_mfma_f32_32x32x16_bf16 v[32:47], v[190:193], v[130:133], v[32:47]
	v_mfma_f32_32x32x16_bf16 v[48:63], v[174:177], v[126:129], v[48:63]
	v_mfma_f32_32x32x16_bf16 v[32:47], v[178:181], v[126:129], v[32:47]
	s_nop 10
	v_max_f32_e32 v174, v48, v48
	v_max_f32_e32 v175, v32, v32
	v_max_f32_e32 v174, v174, v175
	v_max3_f32 v174, v174, v49, v33
	v_max3_f32 v174, v174, v50, v34
	v_max3_f32 v174, v174, v51, v35
	v_max3_f32 v174, v174, v52, v36
	v_max3_f32 v174, v174, v53, v37
	v_max3_f32 v174, v174, v54, v38
	v_max3_f32 v174, v174, v55, v39
	v_max3_f32 v174, v174, v56, v40
	v_max3_f32 v174, v174, v57, v41
	v_max3_f32 v174, v174, v58, v42
	v_max3_f32 v174, v174, v59, v43
	v_max3_f32 v174, v174, v60, v44
	v_max3_f32 v174, v174, v61, v45
	v_max3_f32 v174, v174, v62, v46
	v_max3_f32 v174, v174, v63, v47
	v_fmamk_f32 v174, v174, 0x3e38aa3b, v64
	ds_bpermute_b32 v175, v235, v174
	s_waitcnt lgkmcnt(0)
	v_max3_f32 v213, v238, v174, v175
	v_cmp_gt_f32_e32 vcc, v213, v238
	s_cbranch_vccz .LBB0_351
	v_sub_f32_e32 v174, v238, v213
	v_exp_f32_e32 v174, v174
	s_nop 0
	v_mul_f32_e32 v237, v237, v174
	v_pk_mul_f32 v[30:31], v[30:31], v[174:175] op_sel_hi:[1,0]
	v_pk_mul_f32 v[28:29], v[28:29], v[174:175] op_sel_hi:[1,0]
	v_pk_mul_f32 v[26:27], v[26:27], v[174:175] op_sel_hi:[1,0]
	v_pk_mul_f32 v[24:25], v[24:25], v[174:175] op_sel_hi:[1,0]
	v_pk_mul_f32 v[22:23], v[22:23], v[174:175] op_sel_hi:[1,0]
	v_pk_mul_f32 v[20:21], v[20:21], v[174:175] op_sel_hi:[1,0]
	v_pk_mul_f32 v[18:19], v[18:19], v[174:175] op_sel_hi:[1,0]
	v_pk_mul_f32 v[16:17], v[16:17], v[174:175] op_sel_hi:[1,0]
	v_pk_mul_f32 v[14:15], v[14:15], v[174:175] op_sel_hi:[1,0]
	v_pk_mul_f32 v[12:13], v[12:13], v[174:175] op_sel_hi:[1,0]
	v_pk_mul_f32 v[10:11], v[10:11], v[174:175] op_sel_hi:[1,0]
	v_pk_mul_f32 v[8:9], v[8:9], v[174:175] op_sel_hi:[1,0]
	v_pk_mul_f32 v[6:7], v[6:7], v[174:175] op_sel_hi:[1,0]
	v_pk_mul_f32 v[4:5], v[4:5], v[174:175] op_sel_hi:[1,0]
	v_pk_mul_f32 v[2:3], v[2:3], v[174:175] op_sel_hi:[1,0]
	v_pk_mul_f32 v[0:1], v[0:1], v[174:175] op_sel_hi:[1,0]

; __device__ __forceinline__ unsigned pk2(float lo, float hi) { return pg8::cvt_pk_bf16(lo, hi); }
; #define SB_() __builtin_amdgcn_sched_barrier(0)
; __device__ __forceinline__ void tile_qk_fast(const KFr& f, const bf16x8 (&qf)[4], const bf16x8& kx0, const bf16x8& kx1, const bf16x8& qx, u32x4 (&pw)[4],
;                                              f32x16& o0, f32x16& o1, float& m, float& l, float off) {
;     ...
;         for (int r = 0; r < 16; ++r) { o0[r] *= alpha; o1[r] *= alpha; }
;     }
;     m = mn;
;     const float sh = off - mn;
;     float rs = 0.f;
; #pragma unroll
;     for (int r = 0; r < 16; ++r) { p0[r] = __builtin_amdgcn_exp2f(fmaf(p0[r], C2, sh)); p1[r] = __builtin_amdgcn_exp2f(fmaf(p1[r], C2, sh)); rs += p0[r] + p1[r]; }
;     l += rs;
;     pw[0] = (u32x4){pk2(p0[0], p0[1]), pk2(p0[2], p0[3]), pk2(p0[4], p0[5]), pk2(p0[6], p0[7])};
;     pw[1] = (u32x4){pk2(p0[8], p0[9]), pk2(p0[10], p0[11]), pk2(p0[12], p0[13]), pk2(p0[14], p0[15])};
;     pw[2] = (u32x4){pk2(p1[0], p1[1]), pk2(p1[2], p1[3]), pk2(p1[4], p1[5]), pk2(p1[6], p1[7])};
;     pw[3] = (u32x4){pk2(p1[8], p1[9]), pk2(p1[10], p1[11]), pk2(p1[12], p1[13]), pk2(p1[14], p1[15])};
; }
; __device__ __forceinline__ void tile_pv(const VFr& f, const u32x4 (&pw)[4], f32x16& o0, f32x16& o1) {
; #pragma unroll
;     for (int ks = 0; ks < 4; ++ks) {
;         const bf16x8 P = __builtin_bit_cast(bf16x8, pw[ks]);
;         o0 = __builtin_amdgcn_mfma_f32_32x32x16_bf16(f.a[0][ks], P, o0, 0, 0, 0);
;         o1 = __builtin_amdgcn_mfma_f32_32x32x16_bf16(f.a[1][ks], P, o1, 0, 0, 0);
; __device__ __forceinline__ void moba_unit(int b, int h, int qb, const bf16* qkv, const bf16* KF, const bf16* VF, bf16* Y, const float* kmean, LAS unsigned char* lds) {
;     ...
;             loadV(v0, vp); loadK(k1, kp); SB_(); tile_qk_fast(k0, qg, kx0, kx1, qx, pw, a0, a1, m2, l2, sl2 * (float)(kq0 + 128)); SB_();
;             tile_pv(v0, pw, a0, a1); SB_();
;             bf16x8 qn[4]; int q2n = 0; bool validn = false;
;             loadV(v0, vp);
;             if (have) { TASK_Q(q2n, validn, qn); kp = (const char*)KFh + (size_t)(4 * n) * 8192 + lane * 16; asm volatile("" : "+v"(kp)); loadK(k0, kp); }
.LBB0_353:
	v_sub_f32_e32 v213, v216, v64
	v_fmamk_f32 v48, v48, 0x3e38aa3b, v213
	v_fmamk_f32 v32, v32, 0x3e38aa3b, v213
	v_fmamk_f32 v49, v49, 0x3e38aa3b, v213
	v_fmamk_f32 v33, v33, 0x3e38aa3b, v213
	v_fmamk_f32 v50, v50, 0x3e38aa3b, v213
	v_fmamk_f32 v34, v34, 0x3e38aa3b, v213
	v_fmamk_f32 v51, v51, 0x3e38aa3b, v213
	v_fmamk_f32 v35, v35, 0x3e38aa3b, v213
	v_fmamk_f32 v52, v52, 0x3e38aa3b, v213
	v_fmamk_f32 v36, v36, 0x3e38aa3b, v213
	v_fmamk_f32 v53, v53, 0x3e38aa3b, v213
	v_fmamk_f32 v37, v37, 0x3e38aa3b, v213
	v_fmamk_f32 v54, v54, 0x3e38aa3b, v213
	v_fmamk_f32 v38, v38, 0x3e38aa3b, v213
	v_fmamk_f32 v55, v55, 0x3e38aa3b, v213
	v_fmamk_f32 v39, v39, 0x3e38aa3b, v213
	v_fmamk_f32 v56, v56, 0x3e38aa3b, v213
	v_fmamk_f32 v40, v40, 0x3e38aa3b, v213
	v_fmamk_f32 v57, v57, 0x3e38aa3b, v213
	v_fmamk_f32 v41, v41, 0x3e38aa3b, v213
	v_fmamk_f32 v58, v58, 0x3e38aa3b, v213
	v_fmamk_f32 v42, v42, 0x3e38aa3b, v213
	v_fmamk_f32 v59, v59, 0x3e38aa3b, v213
	v_fmamk_f32 v43, v43, 0x3e38aa3b, v213
	v_fmamk_f32 v60, v60, 0x3e38aa3b, v213
	v_fmamk_f32 v44, v44, 0x3e38aa3b, v213
	v_fmamk_f32 v61, v61, 0x3e38aa3b, v213
	v_fmamk_f32 v45, v45, 0x3e38aa3b, v213
	v_fmamk_f32 v62, v62, 0x3e38aa3b, v213
	v_fmamk_f32 v46, v46, 0x3e38aa3b, v213
	v_fmamk_f32 v63, v63, 0x3e38aa3b, v213
	v_fmac_f32_e32 v213, 0x3e38aa3b, v47
	v_exp_f32_e32 v48, v48
	v_exp_f32_e32 v32, v32
	v_exp_f32_e32 v49, v49
	v_exp_f32_e32 v33, v33
	v_exp_f32_e32 v50, v50
	v_exp_f32_e32 v34, v34
	v_exp_f32_e32 v51, v51
	v_exp_f32_e32 v35, v35
	v_exp_f32_e32 v52, v52
	v_exp_f32_e32 v36, v36
	v_exp_f32_e32 v53, v53
	v_exp_f32_e32 v37, v37
	v_exp_f32_e32 v54, v54
	v_exp_f32_e32 v38, v38
	v_exp_f32_e32 v55, v55
	v_exp_f32_e32 v39, v39
	v_exp_f32_e32 v56, v56
	v_exp_f32_e32 v40, v40
	v_exp_f32_e32 v57, v57
	v_exp_f32_e32 v41, v41
	v_exp_f32_e32 v58, v58
	v_exp_f32_e32 v42, v42
	v_exp_f32_e32 v59, v59
	v_exp_f32_e32 v43, v43
	v_exp_f32_e32 v60, v60
	v_exp_f32_e32 v44, v44
	v_exp_f32_e32 v61, v61
	v_exp_f32_e32 v45, v45
	v_exp_f32_e32 v62, v62
	v_exp_f32_e32 v46, v46
	v_exp_f32_e32 v63, v63
	v_exp_f32_e32 v47, v213
	v_cvt_pk_bf16_f32 v222, v48, v49
	v_cvt_pk_bf16_f32 v223, v50, v51
	v_cvt_pk_bf16_f32 v224, v52, v53
	v_cvt_pk_bf16_f32 v225, v54, v55
	v_cvt_pk_bf16_f32 v238, v56, v57
	v_cvt_pk_bf16_f32 v239, v58, v59
	v_cvt_pk_bf16_f32 v240, v60, v61
	v_cvt_pk_bf16_f32 v241, v62, v63
	v_cvt_pk_bf16_f32 v242, v32, v33
	v_cvt_pk_bf16_f32 v243, v34, v35
	v_cvt_pk_bf16_f32 v244, v36, v37
	v_cvt_pk_bf16_f32 v245, v38, v39
	v_cvt_pk_bf16_f32 v246, v40, v41
	v_cvt_pk_bf16_f32 v247, v42, v43
	v_cvt_pk_bf16_f32 v248, v44, v45
	v_cvt_pk_bf16_f32 v249, v46, v47
	s_waitcnt vmcnt(0)
	v_mfma_f32_32x32x16_bf16 v[16:31], v[162:165], v[222:225], v[16:31]
	v_mfma_f32_32x32x16_bf16 v[0:15], v[174:177], v[222:225], v[0:15]
	v_mfma_f32_32x32x16_bf16 v[16:31], v[154:157], v[238:241], v[16:31]
	v_mfma_f32_32x32x16_bf16 v[0:15], v[166:169], v[238:241], v[0:15]
	v_mfma_f32_32x32x16_bf16 v[16:31], v[146:149], v[242:245], v[16:31]
	v_mfma_f32_32x32x16_bf16 v[0:15], v[158:161], v[242:245], v[0:15]
	v_mfma_f32_32x32x16_bf16 v[16:31], v[142:145], v[246:249], v[16:31]
	v_mfma_f32_32x32x16_bf16 v[0:15], v[150:153], v[246:249], v[0:15]
	v_lshl_add_u64 v[216:217], v[218:219], 0, s[56:57]
	global_load_dwordx4 v[162:165], v[218:219], off
	global_load_dwordx4 v[154:157], v[218:219], off offset:1024
	global_load_dwordx4 v[146:149], v[218:219], off offset:2048
	global_load_dwordx4 v[142:145], v[218:219], off offset:3072
	global_load_dwordx4 v[174:177], v[216:217], off
	global_load_dwordx4 v[166:169], v[216:217], off offset:1024
	global_load_dwordx4 v[158:161], v[216:217], off offset:2048
	global_load_dwordx4 v[150:153], v[216:217], off offset:3072
	v_lshl_add_u64 v[216:217], v[216:217], 0, s[56:57]
	s_andn2_b64 vcc, exec, s[14:15]
	s_cbranch_vccnz .LBB0_355
	s_lshl_b32 s2, s26, 5
	v_or_b32_e32 v78, s2, v232
	s_lshl_b32 s3, s25, 8
	v_mov_b32_e32 v79, s2
	v_cmp_lt_i32_e32 vcc, v78, v231
	s_add_i32 s2, s3, 0
	v_mov_b32_e32 v213, v65
	v_cndmask_b32_e32 v78, v79, v78, vcc
	v_add_u32_e32 v78, s2, v78
	v_add_u32_e32 v78, 0x1b000, v78
	ds_read_u8 v216, v78
	s_movk_i32 s2, 0x1e00
	s_waitcnt lgkmcnt(0)
	v_or_b32_e32 v78, s22, v216
	v_or_b32_e32 v80, s6, v78
	v_mov_b64_e32 v[78:79], s[36:37]
	v_mad_u64_u32 v[78:79], s[2:3], v80, s2, v[78:79]
	v_mad_i32_i24 v79, s7, v226, v79
	v_lshl_add_u64 v[78:79], v[78:79], 0, s[46:47]
	v_lshl_add_u64 v[78:79], v[78:79], 0, v[212:213]
	s_mov_b64 s[2:3], 0x1200
	v_lshl_add_u64 v[90:91], v[78:79], 0, s[2:3]
	s_movk_i32 s2, 0x1000
	v_add_co_u32_e64 v86, s[2:3], s2, v78
	s_nop 1
	v_addc_co_u32_e64 v87, s[2:3], 0, v79, s[2:3]
	s_lshl_b32 s2, s25, 2
	s_ashr_i32 s3, s2, 31
	s_lshl_b64 s[2:3], s[2:3], 13
	v_lshl_add_u64 v[110:111], v[208:209], 0, s[2:3]
	global_load_dwordx4 v[78:81], v[90:91], off offset:32
	global_load_dwordx4 v[82:85], v[90:91], off offset:64
	s_nop 0
	global_load_dwordx4 v[86:89], v[86:87], off offset:512
	s_nop 0
	global_load_dwordx4 v[90:93], v[90:91], off offset:96
	global_load_dwordx4 v[106:109], v[110:111], off
	global_load_dwordx4 v[102:105], v[110:111], off offset:1024
	global_load_dwordx4 v[98:101], v[110:111], off offset:2048
	global_load_dwordx4 v[94:97], v[110:111], off offset:3072
	v_lshl_add_u64 v[214:215], v[110:111], 0, s[56:57]
	global_load_dwordx4 v[122:125], v[214:215], off
	global_load_dwordx4 v[118:121], v[214:215], off offset:1024
	global_load_dwordx4 v[114:117], v[214:215], off offset:2048
	global_load_dwordx4 v[110:113], v[214:215], off offset:3072
	v_lshl_add_u64 v[214:215], v[214:215], 0, s[56:57]
	s_and_b64 s[2:3], vcc, exec
	s_branch .LBB0_356

; template <int MASK>
; __device__ __forceinline__ void tile_qk(const KFr& f, const bf16x8 (&qf)[4], u32x4 (&pw)[4], f32x16& o0, f32x16& o1, float& m, float& l, int kq, float sl2, int lane) {
;     const int hi = lane >> 5;
;     f32x16 p0, p1;
; #pragma unroll
;     for (int r = 0; r < 16; ++r) { p0[r] = 0.f; p1[r] = 0.f; }
; #pragma unroll
;     for (int d0 = 0; d0 < 4; ++d0) {
;         p0 = __builtin_amdgcn_mfma_f32_32x32x16_bf16(f.a[0][d0], qf[d0], p0, 0, 0, 0);
;         p1 = __builtin_amdgcn_mfma_f32_32x32x16_bf16(f.a[1][d0], qf[d0], p1, 0, 0, 0);
;     }
;     constexpr float C2 = 0.125f * LOG2E;
;     const int dk0 = kq + 4 * hi;
;     float sl = sl2; asm volatile("" : "+v"(sl));
;     const float base = sl * (float)dk0;
;     const float NEG = -INFINITY;
;     float mx = NEG;
; #pragma unroll
;     for (int r = 0; r < 16; ++r) {
;         const int kk = (r & 3) + 8 * (r >> 2);
;         float t0 = fmaf(p0[r], C2, fmaf((float)kk, sl, base)), t1 = fmaf(p1[r], C2, fmaf((float)(kk + 32), sl, base));
;         if (MASK == 1) { if (dk0 + kk > 0) t0 = NEG; if (dk0 + kk + 32 > 0) t1 = NEG; }
;         p0[r] = t0; p1[r] = t1; mx = fmaxf(mx, fmaxf(t0, t1));
; __device__ __forceinline__ void moba_unit(int b, int h, int qb, const bf16* qkv, const bf16* KF, const bf16* VF, bf16* Y, const float* kmean, LAS unsigned char* lds) {
;     ...
;         for (int i = 0; i < nown; ++i) {
;             loadK(k0, kp); loadV(v0, vp);
;             tile_qk<1>(k0, qo, pw, o0, o1, m, l, 64 * i - qloc, sl2, lane); tile_pv(v0, pw, o0, o1);
.LBB0_363:
	v_lshl_add_u64 v[40:41], v[118:119], 0, s[56:57]
	v_mov_b32_e32 v124, v32
	global_load_dwordx4 v[32:35], v[118:119], off
	global_load_dwordx4 v[126:129], v[118:119], off offset:1024
	global_load_dwordx4 v[130:133], v[118:119], off offset:2048
	global_load_dwordx4 v[134:137], v[118:119], off offset:3072
	global_load_dwordx4 v[36:39], v[40:41], off
	global_load_dwordx4 v[138:141], v[40:41], off offset:1024
	global_load_dwordx4 v[142:145], v[40:41], off offset:2048
	global_load_dwordx4 v[146:149], v[40:41], off offset:3072
	v_lshl_add_u64 v[118:119], v[40:41], 0, s[56:57]
	v_lshl_add_u64 v[40:41], v[120:121], 0, s[56:57]
	v_mov_b32_e32 v123, v50
	global_load_dwordx4 v[94:97], v[120:121], off
	global_load_dwordx4 v[90:93], v[120:121], off offset:1024
	global_load_dwordx4 v[86:89], v[120:121], off offset:2048
	global_load_dwordx4 v[82:85], v[120:121], off offset:3072
	global_load_dwordx4 v[110:113], v[40:41], off
	global_load_dwordx4 v[106:109], v[40:41], off offset:1024
	global_load_dwordx4 v[102:105], v[40:41], off offset:2048
	global_load_dwordx4 v[98:101], v[40:41], off offset:3072
	v_lshl_add_u64 v[120:121], v[40:41], 0, s[56:57]
	v_cmp_gt_i32_e32 vcc, 1, v117
	s_add_i32 s0, s0, -1
	s_cmp_eq_u32 s0, 0
	s_waitcnt vmcnt(0) lgkmcnt(0)
	v_mfma_f32_32x32x16_bf16 v[48:63], v[32:35], v[78:81], 0
	v_mfma_f32_32x32x16_bf16 v[32:47], v[36:39], v[78:81], 0
	v_mfma_f32_32x32x16_bf16 v[48:63], v[126:129], v[70:73], v[48:63]
	v_cvt_f32_i32_e32 v126, v117
	v_mov_b32_e32 v129, v230
	v_mfma_f32_32x32x16_bf16 v[32:47], v[138:141], v[70:73], v[32:47]
	v_mfma_f32_32x32x16_bf16 v[48:63], v[130:133], v[66:69], v[48:63]
	v_mul_f32_e32 v130, v129, v126
	v_fma_f32 v125, 0, v129, v130
	v_fmamk_f32 v127, v129, 0x42000000, v130
	v_fma_f32 v126, v129, v126, v129
	v_fmamk_f32 v128, v129, 0x420c0000, v130
	v_mfma_f32_32x32x16_bf16 v[32:47], v[142:145], v[66:69], v[32:47]
	v_mfma_f32_32x32x16_bf16 v[48:63], v[134:137], v[74:77], v[48:63]
	v_mfma_f32_32x32x16_bf16 v[32:47], v[146:149], v[74:77], v[32:47]
	s_nop 10
	v_fmac_f32_e32 v125, 0x3e38aa3b, v48
	v_cndmask_b32_e32 v48, v228, v125, vcc
	v_cmp_gt_i32_e32 vcc, s2, v117
	v_fmac_f32_e32 v126, 0x3e38aa3b, v49
	v_fmac_f32_e32 v127, 0x3e38aa3b, v32
	v_cndmask_b32_e32 v125, v228, v127, vcc
	v_fmamk_f32 v127, v129, 0x42040000, v130
	v_cmp_gt_i32_e32 vcc, 0, v117
	v_fmac_f32_e32 v127, 0x3e38aa3b, v33
	v_max_f32_e32 v32, v48, v125
	v_cndmask_b32_e32 v49, v228, v126, vcc
	v_cmp_gt_i32_e32 vcc, s75, v117
	v_fmac_f32_e32 v128, 0x3e38aa3b, v35
	v_fmamk_f32 v35, v129, 0x42240000, v130
	v_cndmask_b32_e32 v126, v228, v127, vcc
	v_max_f32_e32 v33, v49, v126
	v_max3_f32 v32, v32, s1, v33
	v_fma_f32 v33, 2.0, v129, v130
	v_fmac_f32_e32 v33, 0x3e38aa3b, v50
	v_fmamk_f32 v127, v129, 0x42080000, v130
	v_cmp_gt_i32_e32 vcc, -1, v117
	v_fmac_f32_e32 v127, 0x3e38aa3b, v34
	v_fmamk_f32 v34, v129, 0x40400000, v130
	v_cndmask_b32_e32 v50, v228, v33, vcc
	v_cmp_gt_i32_e32 vcc, s72, v117
	v_fmac_f32_e32 v34, 0x3e38aa3b, v51
	v_fmac_f32_e32 v35, 0x3e38aa3b, v37
	v_cndmask_b32_e32 v127, v228, v127, vcc
	v_cmp_gt_i32_e32 vcc, -2, v117
	v_max_f32_e32 v33, v50, v127
	s_nop 0
	v_cndmask_b32_e32 v51, v228, v34, vcc
	v_cmp_gt_i32_e32 vcc, s74, v117
	s_nop 1
	v_cndmask_b32_e32 v128, v228, v128, vcc
	v_max_f32_e32 v34, v51, v128
	v_max3_f32 v32, v32, v33, v34
	v_fmamk_f32 v33, v129, 0x41000000, v130
	v_fmac_f32_e32 v33, 0x3e38aa3b, v52
	v_fmamk_f32 v34, v129, 0x42200000, v130
	v_cmp_gt_i32_e32 vcc, -7, v117
	v_fmac_f32_e32 v34, 0x3e38aa3b, v36
	s_nop 0
	v_cndmask_b32_e32 v36, v228, v33, vcc
	v_cmp_gt_i32_e32 vcc, s3, v117
	s_nop 1
	v_cndmask_b32_e32 v52, v228, v34, vcc
	v_fmamk_f32 v34, v129, 0x41100000, v130
	v_fmac_f32_e32 v34, 0x3e38aa3b, v53
	v_cmp_gt_i32_e32 vcc, -8, v117
	v_max_f32_e32 v33, v36, v52
	s_nop 0
	v_cndmask_b32_e32 v37, v228, v34, vcc
	v_cmp_gt_i32_e32 vcc, s78, v117
	s_nop 1
	v_cndmask_b32_e32 v53, v228, v35, vcc
	v_max_f32_e32 v34, v37, v53
	v_max3_f32 v32, v32, v33, v34
	v_fmamk_f32 v33, v129, 0x41200000, v130
	v_fmac_f32_e32 v33, 0x3e38aa3b, v54
	v_fmamk_f32 v34, v129, 0x42280000, v130
	v_cmp_gt_i32_e32 vcc, -9, v117
	v_fmac_f32_e32 v34, 0x3e38aa3b, v38
	v_fmamk_f32 v35, v129, 0x422c0000, v130
	v_cndmask_b32_e32 v38, v228, v33, vcc
	v_cmp_gt_i32_e32 vcc, s80, v117
	v_fmac_f32_e32 v35, 0x3e38aa3b, v39
	s_nop 0
	v_cndmask_b32_e32 v54, v228, v34, vcc
	v_fmamk_f32 v34, v129, 0x41300000, v130
	v_fmac_f32_e32 v34, 0x3e38aa3b, v55
	v_cmp_gt_i32_e32 vcc, -10, v117
	v_max_f32_e32 v33, v38, v54
	s_nop 0
	v_cndmask_b32_e32 v39, v228, v34, vcc
	v_cmp_gt_i32_e32 vcc, s73, v117
	s_nop 1
	v_cndmask_b32_e32 v55, v228, v35, vcc
	v_max_f32_e32 v34, v39, v55
	v_max3_f32 v32, v32, v33, v34
	v_fmamk_f32 v33, v129, 0x41800000, v130
	v_fmac_f32_e32 v33, 0x3e38aa3b, v56
	v_fmamk_f32 v34, v129, 0x42400000, v130
	v_cmp_gt_i32_e32 vcc, -15, v117
	v_fmac_f32_e32 v34, 0x3e38aa3b, v40
	v_fmamk_f32 v35, v129, 0x42440000, v130
	v_cndmask_b32_e32 v40, v228, v33, vcc
	v_cmp_gt_i32_e32 vcc, s44, v117
	v_fmac_f32_e32 v35, 0x3e38aa3b, v41
	s_nop 0
	v_cndmask_b32_e32 v56, v228, v34, vcc
	v_fmamk_f32 v34, v129, 0x41880000, v130
	v_fmac_f32_e32 v34, 0x3e38aa3b, v57
	v_cmp_gt_i32_e32 vcc, -16, v117
	v_max_f32_e32 v33, v40, v56
	s_nop 0
	v_cndmask_b32_e32 v41, v228, v34, vcc
	v_cmp_gt_i32_e32 vcc, s76, v117
	s_nop 1
	v_cndmask_b32_e32 v57, v228, v35, vcc
	v_max_f32_e32 v34, v41, v57
	v_max3_f32 v32, v32, v33, v34
	v_fmamk_f32 v33, v129, 0x41900000, v130
	v_fmac_f32_e32 v33, 0x3e38aa3b, v58
	v_fmamk_f32 v34, v129, 0x42480000, v130
	v_cmp_gt_i32_e32 vcc, s88, v117
	v_fmac_f32_e32 v34, 0x3e38aa3b, v42
	v_fmamk_f32 v35, v129, 0x424c0000, v130
	v_cndmask_b32_e32 v42, v228, v33, vcc
; template <int MASK>
; __device__ __forceinline__ void tile_qk(const KFr& f, const bf16x8 (&qf)[4], u32x4 (&pw)[4], f32x16& o0, f32x16& o1, float& m, float& l, int kq, float sl2, int lane) {
;     ...
; #pragma unroll
;     for (int r = 0; r < 16; ++r) {
;         const int kk = (r & 3) + 8 * (r >> 2);
;         float t0 = fmaf(p0[r], C2, fmaf((float)kk, sl, base)), t1 = fmaf(p1[r], C2, fmaf((float)(kk + 32), sl, base));
;         if (MASK == 1) { if (dk0 + kk > 0) t0 = NEG; if (dk0 + kk + 32 > 0) t1 = NEG; }
;         p0[r] = t0; p1[r] = t1; mx = fmaxf(mx, fmaxf(t0, t1));
;     }
;     mx = fmaxf(mx, __shfl_xor(mx, 32));
	v_cmp_gt_i32_e32 vcc, s77, v117
	v_fmac_f32_e32 v35, 0x3e38aa3b, v43
	s_nop 0
	v_cndmask_b32_e32 v58, v228, v34, vcc
	v_fmamk_f32 v34, v129, 0x41980000, v130
	v_fmac_f32_e32 v34, 0x3e38aa3b, v59
	v_cmp_gt_i32_e32 vcc, s90, v117
	v_max_f32_e32 v33, v42, v58
	s_nop 0
	v_cndmask_b32_e32 v43, v228, v34, vcc
	v_cmp_gt_i32_e32 vcc, s79, v117
	s_nop 1
	v_cndmask_b32_e32 v59, v228, v35, vcc
	v_max_f32_e32 v34, v43, v59
	v_max3_f32 v32, v32, v33, v34
	v_fmamk_f32 v33, v129, 0x41c00000, v130
	v_fmac_f32_e32 v33, 0x3e38aa3b, v60
	v_fmamk_f32 v34, v129, 0x42600000, v130
	v_cmp_gt_i32_e32 vcc, s45, v117
	v_fmac_f32_e32 v34, 0x3e38aa3b, v44
	v_fmamk_f32 v35, v129, 0x42640000, v130
	v_cndmask_b32_e32 v44, v228, v33, vcc
	v_cmp_gt_i32_e32 vcc, s52, v117
	v_fmac_f32_e32 v35, 0x3e38aa3b, v45
	s_nop 0
	v_cndmask_b32_e32 v60, v228, v34, vcc
	v_fmamk_f32 v34, v129, 0x41c80000, v130
	v_fmac_f32_e32 v34, 0x3e38aa3b, v61
	v_cmp_gt_i32_e32 vcc, s94, v117
	v_max_f32_e32 v33, v44, v60
	s_nop 0
	v_cndmask_b32_e32 v45, v228, v34, vcc
	v_cmp_gt_i32_e32 vcc, s81, v117
	s_nop 1
	v_cndmask_b32_e32 v61, v228, v35, vcc
	v_max_f32_e32 v34, v45, v61
	v_max3_f32 v32, v32, v33, v34
	v_fmamk_f32 v33, v129, 0x41d00000, v130
	v_fmac_f32_e32 v33, 0x3e38aa3b, v62
	v_fmamk_f32 v34, v129, 0x42680000, v130
	v_cmp_gt_i32_e32 vcc, s96, v117
	v_fmac_f32_e32 v34, 0x3e38aa3b, v46
	s_nop 0
	v_cndmask_b32_e32 v46, v228, v33, vcc
	v_cmp_gt_i32_e32 vcc, s82, v117
	s_nop 1
	v_cndmask_b32_e32 v62, v228, v34, vcc
	v_fmamk_f32 v34, v129, 0x41d80000, v130
	v_fmac_f32_e32 v34, 0x3e38aa3b, v63
	v_fmac_f32_e32 v130, 0x426c0000, v129
	v_cmp_gt_i32_e32 vcc, s83, v117
	v_fmac_f32_e32 v130, 0x3e38aa3b, v47
	v_max_f32_e32 v33, v46, v62
	v_cndmask_b32_e32 v47, v228, v34, vcc
	v_cmp_gt_i32_e32 vcc, s84, v117
	v_add_u32_e32 v117, 64, v117
	s_nop 0
	v_cndmask_b32_e32 v63, v228, v130, vcc
	v_max_f32_e32 v34, v47, v63
	v_max3_f32 v32, v32, v33, v34
	v_mbcnt_hi_u32_b32 v33, -1, v220
	v_and_b32_e32 v35, 64, v33
	v_xor_b32_e32 v34, 32, v33
	v_add_u32_e32 v35, 64, v35
	v_cmp_lt_i32_e32 vcc, v34, v35
	s_nop 1
	v_cndmask_b32_e32 v129, v33, v34, vcc
	v_lshlrev_b32_e32 v129, 2, v129
	ds_bpermute_b32 v129, v129, v32
	s_waitcnt lgkmcnt(0)
; __device__ __forceinline__ unsigned pk2(float lo, float hi) { return pg8::cvt_pk_bf16(lo, hi); }
; template <int MASK>
; __device__ __forceinline__ void tile_qk(const KFr& f, const bf16x8 (&qf)[4], u32x4 (&pw)[4], f32x16& o0, f32x16& o1, float& m, float& l, int kq, float sl2, int lane) {
;     ...
;     mx = fmaxf(mx, __shfl_xor(mx, 32));
;     const float mn = fmaxf(m, mx), alpha = __builtin_amdgcn_exp2f(m - mn); m = mn;
;     float rs = 0.f;
; #pragma unroll
;     for (int r = 0; r < 16; ++r) { p0[r] = __builtin_amdgcn_exp2f(p0[r] - mn); p1[r] = __builtin_amdgcn_exp2f(p1[r] - mn); rs += p0[r] + p1[r]; }
;     l = l * alpha + rs;
; #pragma unroll
;     for (int r = 0; r < 16; ++r) { o0[r] *= alpha; o1[r] *= alpha; }
;     pw[0] = (u32x4){pk2(p0[0], p0[1]), pk2(p0[2], p0[3]), pk2(p0[4], p0[5]), pk2(p0[6], p0[7])};
;     pw[1] = (u32x4){pk2(p0[8], p0[9]), pk2(p0[10], p0[11]), pk2(p0[12], p0[13]), pk2(p0[14], p0[15])};
;     pw[2] = (u32x4){pk2(p1[0], p1[1]), pk2(p1[2], p1[3]), pk2(p1[4], p1[5]), pk2(p1[6], p1[7])};
;     pw[3] = (u32x4){pk2(p1[8], p1[9]), pk2(p1[10], p1[11]), pk2(p1[12], p1[13]), pk2(p1[14], p1[15])};
; __device__ __forceinline__ void tile_pv(const VFr& f, const u32x4 (&pw)[4], f32x16& o0, f32x16& o1) {
; #pragma unroll
;     for (int ks = 0; ks < 4; ++ks) {
;         const bf16x8 P = __builtin_bit_cast(bf16x8, pw[ks]);
;         o0 = __builtin_amdgcn_mfma_f32_32x32x16_bf16(f.a[0][ks], P, o0, 0, 0, 0);
;         o1 = __builtin_amdgcn_mfma_f32_32x32x16_bf16(f.a[1][ks], P, o1, 0, 0, 0);
;     }
	v_max3_f32 v32, v124, v32, v129
	v_sub_f32_e32 v48, v48, v32
	v_exp_f32_e32 v130, v48
	v_sub_f32_e32 v48, v125, v32
	v_sub_f32_e32 v49, v49, v32
	v_exp_f32_e32 v131, v48
	v_exp_f32_e32 v132, v49
	v_sub_f32_e32 v49, v126, v32
	v_exp_f32_e32 v133, v49
	v_add_f32_e32 v48, v131, v130
	v_add_f32_e32 v48, 0, v48
	v_sub_f32_e32 v36, v36, v32
	v_add_f32_e32 v49, v133, v132
	v_add_f32_e32 v48, v49, v48
	v_sub_f32_e32 v49, v50, v32
	v_exp_f32_e32 v134, v49
	v_sub_f32_e32 v49, v127, v32
	v_exp_f32_e32 v135, v49
	v_sub_f32_e32 v129, v124, v32
	v_add_f32_e32 v49, v135, v134
	v_add_f32_e32 v48, v49, v48
	v_sub_f32_e32 v49, v51, v32
	v_exp_f32_e32 v51, v49
	v_sub_f32_e32 v49, v128, v32
	v_exp_f32_e32 v128, v49
	s_nop 0
	v_add_f32_e32 v49, v128, v51
	v_add_f32_e32 v50, v49, v48
	v_exp_f32_e32 v49, v36
	v_sub_f32_e32 v36, v52, v32
	v_exp_f32_e32 v125, v36
	v_sub_f32_e32 v36, v37, v32
	v_exp_f32_e32 v48, v36
	v_sub_f32_e32 v36, v53, v32
	v_exp_f32_e32 v124, v36
	s_nop 0
	v_pk_add_f32 v[36:37], v[124:125], v[48:49]
	s_nop 0
	v_add_f32_e32 v37, v37, v50
	v_add_f32_e32 v50, v36, v37
	v_sub_f32_e32 v36, v38, v32
	v_exp_f32_e32 v37, v36
	v_sub_f32_e32 v36, v54, v32
	v_exp_f32_e32 v53, v36
	v_sub_f32_e32 v36, v39, v32
	v_sub_f32_e32 v38, v55, v32
	v_exp_f32_e32 v36, v36
	v_exp_f32_e32 v52, v38
	s_nop 0
	v_pk_add_f32 v[38:39], v[52:53], v[36:37]
	s_nop 0
	v_add_f32_e32 v39, v39, v50
	v_add_f32_e32 v50, v38, v39
	v_sub_f32_e32 v38, v40, v32
	v_exp_f32_e32 v39, v38
	v_sub_f32_e32 v38, v56, v32
	v_exp_f32_e32 v55, v38
	v_sub_f32_e32 v38, v41, v32
	v_sub_f32_e32 v40, v57, v32
	v_exp_f32_e32 v38, v38
	v_exp_f32_e32 v54, v40
	v_pk_mov_b32 v[52:53], v[52:53], v[52:53] op_sel:[1,0]
	v_pk_add_f32 v[40:41], v[54:55], v[38:39]
	s_nop 0
	v_add_f32_e32 v41, v41, v50
	v_add_f32_e32 v50, v40, v41
	v_sub_f32_e32 v40, v42, v32
	v_exp_f32_e32 v41, v40
	v_sub_f32_e32 v40, v58, v32
	v_exp_f32_e32 v57, v40
	v_sub_f32_e32 v40, v43, v32
	v_sub_f32_e32 v42, v59, v32
	v_exp_f32_e32 v40, v40
	v_exp_f32_e32 v56, v42
	v_pk_mov_b32 v[54:55], v[54:55], v[54:55] op_sel:[1,0]
	v_pk_mov_b32 v[126:127], v[40:41], v[40:41] op_sel:[1,0]
	v_pk_add_f32 v[42:43], v[56:57], v[40:41]
	v_cvt_pk_bf16_f32 v41, v126, v127
	v_add_f32_e32 v43, v43, v50
	v_add_f32_e32 v50, v42, v43
	v_sub_f32_e32 v42, v44, v32
	v_exp_f32_e32 v43, v42
	v_sub_f32_e32 v42, v60, v32
	v_exp_f32_e32 v59, v42
	v_sub_f32_e32 v42, v45, v32
	v_sub_f32_e32 v44, v61, v32
	v_exp_f32_e32 v42, v42
	v_exp_f32_e32 v58, v44
	v_pk_mov_b32 v[56:57], v[56:57], v[56:57] op_sel:[1,0]
	v_pk_add_f32 v[44:45], v[58:59], v[42:43]
	s_nop 0
	v_add_f32_e32 v45, v45, v50
	v_add_f32_e32 v50, v44, v45
	v_sub_f32_e32 v44, v46, v32
	v_exp_f32_e32 v45, v44
	v_sub_f32_e32 v44, v62, v32
	v_exp_f32_e32 v61, v44
	v_sub_f32_e32 v44, v47, v32
	v_sub_f32_e32 v46, v63, v32
	v_exp_f32_e32 v44, v44
	v_exp_f32_e32 v60, v46
	v_pk_mov_b32 v[62:63], v[36:37], v[36:37] op_sel:[1,0]
	v_cvt_pk_bf16_f32 v36, v130, v132
	v_cvt_pk_bf16_f32 v37, v134, v51
	v_pk_add_f32 v[46:47], v[60:61], v[44:45]
	v_pk_mov_b32 v[42:43], v[42:43], v[42:43] op_sel:[1,0]
	v_add_f32_e32 v47, v47, v50
	v_add_f32_e32 v50, v46, v47
	v_exp_f32_e32 v46, v129
	v_pk_mov_b32 v[44:45], v[44:45], v[44:45] op_sel:[1,0]
	v_cvt_pk_bf16_f32 v42, v42, v43
	v_cvt_pk_bf16_f32 v43, v44, v45
	v_fmac_f32_e32 v50, v123, v46
	v_pk_mul_f32 v[30:31], v[30:31], v[46:47] op_sel_hi:[1,0]
	v_pk_mul_f32 v[28:29], v[28:29], v[46:47] op_sel_hi:[1,0]
	v_pk_mul_f32 v[26:27], v[26:27], v[46:47] op_sel_hi:[1,0]
	v_pk_mul_f32 v[24:25], v[24:25], v[46:47] op_sel_hi:[1,0]
	v_pk_mul_f32 v[22:23], v[22:23], v[46:47] op_sel_hi:[1,0]
	v_pk_mul_f32 v[20:21], v[20:21], v[46:47] op_sel_hi:[1,0]
	v_pk_mul_f32 v[18:19], v[18:19], v[46:47] op_sel_hi:[1,0]
	v_pk_mul_f32 v[16:17], v[16:17], v[46:47] op_sel_hi:[1,0]
	v_pk_mul_f32 v[14:15], v[14:15], v[46:47] op_sel_hi:[1,0]
	v_pk_mul_f32 v[12:13], v[12:13], v[46:47] op_sel_hi:[1,0]
	v_pk_mul_f32 v[10:11], v[10:11], v[46:47] op_sel_hi:[1,0]
	v_pk_mul_f32 v[8:9], v[8:9], v[46:47] op_sel_hi:[1,0]
	v_pk_mul_f32 v[6:7], v[6:7], v[46:47] op_sel_hi:[1,0]
	v_pk_mul_f32 v[4:5], v[4:5], v[46:47] op_sel_hi:[1,0]
	v_pk_mul_f32 v[2:3], v[2:3], v[46:47] op_sel_hi:[1,0]
	v_pk_mul_f32 v[0:1], v[0:1], v[46:47] op_sel_hi:[1,0]
	v_pk_mov_b32 v[46:47], v[48:49], v[48:49] op_sel:[1,0]
	v_pk_mov_b32 v[48:49], v[124:125], v[124:125] op_sel:[1,0]
	v_pk_mov_b32 v[124:125], v[38:39], v[38:39] op_sel:[1,0]
	v_cvt_pk_bf16_f32 v38, v46, v47
	v_cvt_pk_bf16_f32 v39, v62, v63
	v_cvt_pk_bf16_f32 v40, v124, v125
	v_cvt_pk_bf16_f32 v44, v131, v133
	v_mfma_f32_32x32x16_bf16 v[16:31], v[94:97], v[36:39], v[16:31]
	v_cvt_pk_bf16_f32 v45, v135, v128
	v_cvt_pk_bf16_f32 v46, v48, v49
	v_cvt_pk_bf16_f32 v47, v52, v53
	v_pk_mov_b32 v[58:59], v[58:59], v[58:59] op_sel:[1,0]
	v_pk_mov_b32 v[60:61], v[60:61], v[60:61] op_sel:[1,0]
	v_cvt_pk_bf16_f32 v52, v54, v55
	v_cvt_pk_bf16_f32 v53, v56, v57
	v_mfma_f32_32x32x16_bf16 v[0:15], v[110:113], v[36:39], v[0:15]
	v_cvt_pk_bf16_f32 v54, v58, v59
	v_cvt_pk_bf16_f32 v55, v60, v61
	v_mfma_f32_32x32x16_bf16 v[16:31], v[90:93], v[40:43], v[16:31]
	v_mfma_f32_32x32x16_bf16 v[0:15], v[106:109], v[40:43], v[0:15]
	v_mfma_f32_32x32x16_bf16 v[16:31], v[86:89], v[44:47], v[16:31]
	v_mfma_f32_32x32x16_bf16 v[0:15], v[102:105], v[44:47], v[0:15]
	v_mfma_f32_32x32x16_bf16 v[16:31], v[82:85], v[52:55], v[16:31]
	v_mfma_f32_32x32x16_bf16 v[0:15], v[98:101], v[52:55], v[0:15]
	s_cbranch_scc0 .LBB0_363
	s_mov_b64 s[0:1], 0
